# DA: softmax scale folded into the q_b projection epilogue (single bf16 rounding), bias (bc - m) injected through the QK MFMA C-in block so exp2 needs no per-element fma; 16 phase-invariant VGPRs parke
# speedup vs baseline: 1.0316x; 1.0153x over previous
; __device__ __forceinline__ unsigned cvtpk(float lo, float hi) { f32x2_t v = {lo, hi}; bf16x2_t b = __builtin_convertvector(v, bf16x2_t); return __builtin_bit_cast(unsigned, b); }
;     __device__ __forceinline__ void operator()(const f32x4 (&acc)[2][2][4][2], const Unit& u, int wr, int wc, int fr, int fq) const {
;         const int row0 = u.pm * BM + wr * 64 + fr; const int col0 = u.pn * BM + wc * 32 + 8 * fq;
; #pragma unroll
;         for (int ai = 0; ai < 2; ++ai)
; #pragma unroll
;             for (int m = 0; m < 4; ++m) {
;                 const int row = row0 + ai * HALF + m * 16;
;                 const f32x4 a = *((const f32x4*)(ssq + (size_t)row * 16) + fq);
;                 float tot = (a[0] + a[1]) + (a[2] + a[3]);
;                 tot = sum_rows4(tot);
;                 const float rs = __builtin_amdgcn_rsqf(tot * (1.0f / 1024.0f) + 1e-6f);
;                 bf16_t* rowp = O + (size_t)row * ldc + col0;
; #pragma unroll
;                 for (int bj = 0; bj < 2; ++bj) { const f32x4 v0 = acc[ai][bj][m][0] * rs, v1 = acc[ai][bj][m][1] * rs;
;                     u32x4 w; w.x = cvtpk(v0[0], v0[1]); w.y = cvtpk(v0[2], v0[3]); w.z = cvtpk(v1[0], v1[1]); w.w = cvtpk(v1[2], v1[3]);
;                     *(u32x4*)(rowp + bj * HALF) = w; }
;                 asm volatile("" ::: "memory"); }
.LBB0_87:
	s_sub_i32 s100, s91, 8
	s_cmp_lt_u32 s100, 2
	s_cselect_b32 s100, 0x3e38aa3b, 1.0
	v_lshl_add_u32 v142, s96, 8, v144
	v_ashrrev_i32_e32 v143, 31, v142
	v_lshlrev_b64 v[148:149], 6, v[142:143]
	v_lshl_add_u64 v[148:149], v[134:135], 0, v[148:149]
	global_load_dwordx4 v[148:151], v[148:149], off
	v_lshl_or_b32 v140, s91, 8, v146
	v_ashrrev_i32_e32 v141, 31, v140
	v_lshlrev_b64 v[140:141], 1, v[140:141]
	s_mov_b64 s[30:31], -1
	s_andn2_b64 vcc, exec, s[36:37]
	s_waitcnt vmcnt(0)
	v_add_f32_e32 v148, v148, v149
	v_add_f32_e32 v149, v150, v151
	v_add_f32_e32 v148, v148, v149
	v_mov_b32_e32 v149, v148
	s_nop 1
	v_permlane16_swap_b32_e32 v148, v149
	v_add_f32_e32 v148, v148, v149
	v_mov_b32_e32 v149, v148
	s_nop 1
	v_permlane32_swap_b32_e32 v148, v149
	v_add_f32_e32 v148, v148, v149
	v_fmamk_f32 v148, v148, 0x3a800000, v206
	v_rsq_f32_e32 v148, v148
	s_nop 0
	v_mul_f32_e32 v148, s100, v148
	v_lshlrev_b64 v[150:151], 13, v[142:143]
	v_lshl_add_u64 v[150:151], s[60:61], 0, v[150:151]
	v_lshl_add_u64 v[150:151], v[150:151], 0, v[140:141]
	v_pk_mul_f32 v[126:127], v[126:127], v[148:149] op_sel_hi:[1,0]
	v_pk_mul_f32 v[124:125], v[124:125], v[148:149] op_sel_hi:[1,0]
	v_pk_mul_f32 v[164:165], v[122:123], v[148:149] op_sel_hi:[1,0]
	v_pk_mul_f32 v[122:123], v[120:121], v[148:149] op_sel_hi:[1,0]
	v_cvt_pk_bf16_f32 v120, v124, v125
	v_cvt_pk_bf16_f32 v121, v126, v127
	v_cvt_pk_bf16_f32 v122, v122, v123
	v_cvt_pk_bf16_f32 v123, v164, v165
	v_pk_mul_f32 v[116:117], v[116:117], v[148:149] op_sel_hi:[1,0]
	global_store_dwordx4 v[150:151], v[120:123], off
	v_pk_mul_f32 v[118:119], v[118:119], v[148:149] op_sel_hi:[1,0]
	s_nop 0
	v_pk_mul_f32 v[120:121], v[114:115], v[148:149] op_sel_hi:[1,0]
	v_pk_mul_f32 v[114:115], v[112:113], v[148:149] op_sel_hi:[1,0]
	v_cvt_pk_bf16_f32 v112, v116, v117
	v_or_b32_e32 v116, 16, v142
	v_cvt_pk_bf16_f32 v113, v118, v119
	v_cvt_pk_bf16_f32 v114, v114, v115
	v_cvt_pk_bf16_f32 v115, v120, v121
	v_ashrrev_i32_e32 v117, 31, v116
	global_store_dwordx4 v[150:151], v[112:115], off offset:256
	s_nop 1
	v_lshlrev_b64 v[112:113], 6, v[116:117]
	v_lshl_add_u64 v[112:113], v[134:135], 0, v[112:113]
	global_load_dwordx4 v[112:115], v[112:113], off
	s_waitcnt vmcnt(0)
	v_add_f32_e32 v112, v112, v113
	v_add_f32_e32 v113, v114, v115
	v_add_f32_e32 v112, v112, v113
	v_mov_b32_e32 v113, v112
	s_nop 1
	v_permlane16_swap_b32_e32 v112, v113
	v_add_f32_e32 v112, v112, v113
	v_mov_b32_e32 v113, v112
	s_nop 1
	v_permlane32_swap_b32_e32 v112, v113
	v_add_f32_e32 v112, v112, v113
	v_fmamk_f32 v112, v112, 0x3a800000, v206
	v_rsq_f32_e32 v112, v112
	s_nop 0
	v_mul_f32_e32 v112, s100, v112
	v_lshlrev_b64 v[114:115], 13, v[116:117]
	v_lshl_add_u64 v[114:115], s[60:61], 0, v[114:115]
	v_lshl_add_u64 v[114:115], v[114:115], 0, v[140:141]
	v_pk_mul_f32 v[110:111], v[110:111], v[112:113] op_sel_hi:[1,0]
	v_pk_mul_f32 v[108:109], v[108:109], v[112:113] op_sel_hi:[1,0]
	v_pk_mul_f32 v[116:117], v[106:107], v[112:113] op_sel_hi:[1,0]
	v_pk_mul_f32 v[106:107], v[104:105], v[112:113] op_sel_hi:[1,0]
	v_cvt_pk_bf16_f32 v104, v108, v109
	v_cvt_pk_bf16_f32 v105, v110, v111
	v_cvt_pk_bf16_f32 v106, v106, v107
	v_cvt_pk_bf16_f32 v107, v116, v117
	v_pk_mul_f32 v[100:101], v[100:101], v[112:113] op_sel_hi:[1,0]
	global_store_dwordx4 v[114:115], v[104:107], off
	v_pk_mul_f32 v[102:103], v[102:103], v[112:113] op_sel_hi:[1,0]
	s_nop 0
	v_pk_mul_f32 v[104:105], v[98:99], v[112:113] op_sel_hi:[1,0]
	v_pk_mul_f32 v[98:99], v[96:97], v[112:113] op_sel_hi:[1,0]
	v_cvt_pk_bf16_f32 v96, v100, v101
	v_or_b32_e32 v100, 32, v142
	v_cvt_pk_bf16_f32 v97, v102, v103
	v_cvt_pk_bf16_f32 v98, v98, v99
	v_cvt_pk_bf16_f32 v99, v104, v105
	v_ashrrev_i32_e32 v101, 31, v100
	global_store_dwordx4 v[114:115], v[96:99], off offset:256
	s_nop 1
	v_lshlrev_b64 v[96:97], 6, v[100:101]
	v_lshl_add_u64 v[96:97], v[134:135], 0, v[96:97]
	global_load_dwordx4 v[96:99], v[96:97], off
	s_waitcnt vmcnt(0)
	v_add_f32_e32 v96, v96, v97
	v_add_f32_e32 v97, v98, v99
	v_add_f32_e32 v96, v96, v97
	v_mov_b32_e32 v97, v96
	s_nop 1
	v_permlane16_swap_b32_e32 v96, v97
	v_add_f32_e32 v96, v96, v97
	v_mov_b32_e32 v97, v96
	s_nop 1
	v_permlane32_swap_b32_e32 v96, v97
	v_add_f32_e32 v96, v96, v97
	v_fmamk_f32 v96, v96, 0x3a800000, v206
	v_rsq_f32_e32 v96, v96
	s_nop 0
	v_mul_f32_e32 v96, s100, v96
	v_lshlrev_b64 v[98:99], 13, v[100:101]
	v_lshl_add_u64 v[98:99], s[60:61], 0, v[98:99]
	v_lshl_add_u64 v[98:99], v[98:99], 0, v[140:141]
	v_pk_mul_f32 v[94:95], v[94:95], v[96:97] op_sel_hi:[1,0]
	v_pk_mul_f32 v[92:93], v[92:93], v[96:97] op_sel_hi:[1,0]
	v_pk_mul_f32 v[100:101], v[90:91], v[96:97] op_sel_hi:[1,0]
	v_pk_mul_f32 v[90:91], v[88:89], v[96:97] op_sel_hi:[1,0]
	v_cvt_pk_bf16_f32 v88, v92, v93
	v_cvt_pk_bf16_f32 v89, v94, v95
	v_cvt_pk_bf16_f32 v90, v90, v91
	v_cvt_pk_bf16_f32 v91, v100, v101
	v_pk_mul_f32 v[84:85], v[84:85], v[96:97] op_sel_hi:[1,0]
	global_store_dwordx4 v[98:99], v[88:91], off
	v_pk_mul_f32 v[86:87], v[86:87], v[96:97] op_sel_hi:[1,0]
	s_nop 0
	v_pk_mul_f32 v[88:89], v[82:83], v[96:97] op_sel_hi:[1,0]
	v_pk_mul_f32 v[82:83], v[80:81], v[96:97] op_sel_hi:[1,0]
	v_cvt_pk_bf16_f32 v80, v84, v85
	v_or_b32_e32 v84, 48, v142
	v_cvt_pk_bf16_f32 v81, v86, v87
	v_cvt_pk_bf16_f32 v82, v82, v83
	v_cvt_pk_bf16_f32 v83, v88, v89
	v_ashrrev_i32_e32 v85, 31, v84
	global_store_dwordx4 v[98:99], v[80:83], off offset:256
	s_nop 1
	v_lshlrev_b64 v[80:81], 6, v[84:85]
	v_lshl_add_u64 v[80:81], v[134:135], 0, v[80:81]
	global_load_dwordx4 v[80:83], v[80:81], off
	s_waitcnt vmcnt(0)
; __device__ __forceinline__ unsigned cvtpk(float lo, float hi) { f32x2_t v = {lo, hi}; bf16x2_t b = __builtin_convertvector(v, bf16x2_t); return __builtin_bit_cast(unsigned, b); }
;     __device__ __forceinline__ void operator()(const f32x4 (&acc)[2][2][4][2], const Unit& u, int wr, int wc, int fr, int fq) const {
;     ...
;             for (int m = 0; m < 4; ++m) {
;                 const int row = row0 + ai * HALF + m * 16;
;                 const f32x4 a = *((const f32x4*)(ssq + (size_t)row * 16) + fq);
;                 float tot = (a[0] + a[1]) + (a[2] + a[3]);
;                 tot = sum_rows4(tot);
;                 const float rs = __builtin_amdgcn_rsqf(tot * (1.0f / 1024.0f) + 1e-6f);
;                 bf16_t* rowp = O + (size_t)row * ldc + col0;
; #pragma unroll
;                 for (int bj = 0; bj < 2; ++bj) { const f32x4 v0 = acc[ai][bj][m][0] * rs, v1 = acc[ai][bj][m][1] * rs;
;                     u32x4 w; w.x = cvtpk(v0[0], v0[1]); w.y = cvtpk(v0[2], v0[3]); w.z = cvtpk(v1[0], v1[1]); w.w = cvtpk(v1[2], v1[3]);
;                     *(u32x4*)(rowp + bj * HALF) = w; }
;                 asm volatile("" ::: "memory"); }
	v_add_f32_e32 v80, v80, v81
	v_add_f32_e32 v81, v82, v83
	v_add_f32_e32 v80, v80, v81
	v_mov_b32_e32 v81, v80
	s_nop 1
	v_permlane16_swap_b32_e32 v80, v81
	v_add_f32_e32 v80, v80, v81
	v_mov_b32_e32 v81, v80
	s_nop 1
	v_permlane32_swap_b32_e32 v80, v81
	v_add_f32_e32 v80, v80, v81
	v_fmamk_f32 v80, v80, 0x3a800000, v206
	v_rsq_f32_e32 v80, v80
	s_nop 0
	v_mul_f32_e32 v80, s100, v80
	v_lshlrev_b64 v[82:83], 13, v[84:85]
	v_lshl_add_u64 v[82:83], s[60:61], 0, v[82:83]
	v_lshl_add_u64 v[82:83], v[82:83], 0, v[140:141]
	v_pk_mul_f32 v[78:79], v[78:79], v[80:81] op_sel_hi:[1,0]
	v_pk_mul_f32 v[76:77], v[76:77], v[80:81] op_sel_hi:[1,0]
	v_pk_mul_f32 v[84:85], v[74:75], v[80:81] op_sel_hi:[1,0]
	v_pk_mul_f32 v[74:75], v[72:73], v[80:81] op_sel_hi:[1,0]
	v_cvt_pk_bf16_f32 v72, v76, v77
	v_cvt_pk_bf16_f32 v73, v78, v79
	v_cvt_pk_bf16_f32 v74, v74, v75
	v_cvt_pk_bf16_f32 v75, v84, v85
	v_pk_mul_f32 v[68:69], v[68:69], v[80:81] op_sel_hi:[1,0]
	global_store_dwordx4 v[82:83], v[72:75], off
	v_pk_mul_f32 v[70:71], v[70:71], v[80:81] op_sel_hi:[1,0]
	s_nop 0
	v_pk_mul_f32 v[72:73], v[66:67], v[80:81] op_sel_hi:[1,0]
	v_pk_mul_f32 v[66:67], v[64:65], v[80:81] op_sel_hi:[1,0]
	v_cvt_pk_bf16_f32 v64, v68, v69
	v_add_u32_e32 v68, 0x80, v142
	v_cvt_pk_bf16_f32 v65, v70, v71
	v_cvt_pk_bf16_f32 v66, v66, v67
	v_cvt_pk_bf16_f32 v67, v72, v73
	v_ashrrev_i32_e32 v69, 31, v68
	global_store_dwordx4 v[82:83], v[64:67], off offset:256
	s_nop 1
	v_lshlrev_b64 v[64:65], 6, v[68:69]
	v_lshl_add_u64 v[64:65], v[134:135], 0, v[64:65]
	global_load_dwordx4 v[64:67], v[64:65], off
	s_waitcnt vmcnt(0)
	v_add_f32_e32 v64, v64, v65
	v_add_f32_e32 v65, v66, v67
	v_add_f32_e32 v64, v64, v65
	v_mov_b32_e32 v65, v64
	s_nop 1
	v_permlane16_swap_b32_e32 v64, v65
	v_add_f32_e32 v64, v64, v65
	v_mov_b32_e32 v65, v64
	s_nop 1
	v_permlane32_swap_b32_e32 v64, v65
	v_add_f32_e32 v64, v64, v65
	v_fmamk_f32 v64, v64, 0x3a800000, v206
	v_rsq_f32_e32 v64, v64
	s_nop 0
	v_mul_f32_e32 v64, s100, v64
	v_lshlrev_b64 v[66:67], 13, v[68:69]
	v_lshl_add_u64 v[66:67], s[60:61], 0, v[66:67]
	v_lshl_add_u64 v[66:67], v[66:67], 0, v[140:141]
	v_pk_mul_f32 v[62:63], v[62:63], v[64:65] op_sel_hi:[1,0]
	v_pk_mul_f32 v[60:61], v[60:61], v[64:65] op_sel_hi:[1,0]
	v_pk_mul_f32 v[68:69], v[58:59], v[64:65] op_sel_hi:[1,0]
	v_pk_mul_f32 v[58:59], v[56:57], v[64:65] op_sel_hi:[1,0]
	v_cvt_pk_bf16_f32 v56, v60, v61
	v_cvt_pk_bf16_f32 v57, v62, v63
	v_cvt_pk_bf16_f32 v58, v58, v59
	v_cvt_pk_bf16_f32 v59, v68, v69
	v_pk_mul_f32 v[52:53], v[52:53], v[64:65] op_sel_hi:[1,0]
	global_store_dwordx4 v[66:67], v[56:59], off
	v_pk_mul_f32 v[54:55], v[54:55], v[64:65] op_sel_hi:[1,0]
	s_nop 0
	v_pk_mul_f32 v[56:57], v[50:51], v[64:65] op_sel_hi:[1,0]
	v_pk_mul_f32 v[50:51], v[48:49], v[64:65] op_sel_hi:[1,0]
	v_cvt_pk_bf16_f32 v48, v52, v53
	v_add_u32_e32 v52, 0x90, v142
	v_cvt_pk_bf16_f32 v49, v54, v55
	v_cvt_pk_bf16_f32 v50, v50, v51
	v_cvt_pk_bf16_f32 v51, v56, v57
	v_ashrrev_i32_e32 v53, 31, v52
	global_store_dwordx4 v[66:67], v[48:51], off offset:256
	s_nop 1
	v_lshlrev_b64 v[48:49], 6, v[52:53]
	v_lshl_add_u64 v[48:49], v[134:135], 0, v[48:49]
	global_load_dwordx4 v[48:51], v[48:49], off
	s_waitcnt vmcnt(0)
; __device__ __forceinline__ unsigned cvtpk(float lo, float hi) { f32x2_t v = {lo, hi}; bf16x2_t b = __builtin_convertvector(v, bf16x2_t); return __builtin_bit_cast(unsigned, b); }
;     __device__ __forceinline__ void operator()(const f32x4 (&acc)[2][2][4][2], const Unit& u, int wr, int wc, int fr, int fq) const {
;     ...
;             for (int m = 0; m < 4; ++m) {
;                 const int row = row0 + ai * HALF + m * 16;
;                 const f32x4 a = *((const f32x4*)(ssq + (size_t)row * 16) + fq);
;                 float tot = (a[0] + a[1]) + (a[2] + a[3]);
;                 tot = sum_rows4(tot);
;                 const float rs = __builtin_amdgcn_rsqf(tot * (1.0f / 1024.0f) + 1e-6f);
;                 bf16_t* rowp = O + (size_t)row * ldc + col0;
; #pragma unroll
;                 for (int bj = 0; bj < 2; ++bj) { const f32x4 v0 = acc[ai][bj][m][0] * rs, v1 = acc[ai][bj][m][1] * rs;
;                     u32x4 w; w.x = cvtpk(v0[0], v0[1]); w.y = cvtpk(v0[2], v0[3]); w.z = cvtpk(v1[0], v1[1]); w.w = cvtpk(v1[2], v1[3]);
;                     *(u32x4*)(rowp + bj * HALF) = w; }
;                 asm volatile("" ::: "memory"); }
	v_add_f32_e32 v48, v48, v49
	v_add_f32_e32 v49, v50, v51
	v_add_f32_e32 v48, v48, v49
	v_mov_b32_e32 v49, v48
	s_nop 1
	v_permlane16_swap_b32_e32 v48, v49
	v_add_f32_e32 v48, v48, v49
	v_mov_b32_e32 v49, v48
	s_nop 1
	v_permlane32_swap_b32_e32 v48, v49
	v_add_f32_e32 v48, v48, v49
	v_fmamk_f32 v48, v48, 0x3a800000, v206
	v_rsq_f32_e32 v48, v48
	s_nop 0
	v_mul_f32_e32 v48, s100, v48
	v_lshlrev_b64 v[50:51], 13, v[52:53]
	v_lshl_add_u64 v[50:51], s[60:61], 0, v[50:51]
	v_lshl_add_u64 v[50:51], v[50:51], 0, v[140:141]
	v_pk_mul_f32 v[46:47], v[46:47], v[48:49] op_sel_hi:[1,0]
	v_pk_mul_f32 v[44:45], v[44:45], v[48:49] op_sel_hi:[1,0]
	v_pk_mul_f32 v[52:53], v[42:43], v[48:49] op_sel_hi:[1,0]
	v_pk_mul_f32 v[42:43], v[40:41], v[48:49] op_sel_hi:[1,0]
	v_cvt_pk_bf16_f32 v40, v44, v45
	v_cvt_pk_bf16_f32 v41, v46, v47
	v_cvt_pk_bf16_f32 v42, v42, v43
	v_cvt_pk_bf16_f32 v43, v52, v53
	v_pk_mul_f32 v[36:37], v[36:37], v[48:49] op_sel_hi:[1,0]
	global_store_dwordx4 v[50:51], v[40:43], off
	v_pk_mul_f32 v[38:39], v[38:39], v[48:49] op_sel_hi:[1,0]
	s_nop 0
	v_pk_mul_f32 v[40:41], v[34:35], v[48:49] op_sel_hi:[1,0]
	v_pk_mul_f32 v[34:35], v[32:33], v[48:49] op_sel_hi:[1,0]
	v_cvt_pk_bf16_f32 v32, v36, v37
	v_add_u32_e32 v36, 0xa0, v142
	v_cvt_pk_bf16_f32 v33, v38, v39
	v_cvt_pk_bf16_f32 v34, v34, v35
	v_cvt_pk_bf16_f32 v35, v40, v41
	v_ashrrev_i32_e32 v37, 31, v36
	global_store_dwordx4 v[50:51], v[32:35], off offset:256
	s_nop 1
	v_lshlrev_b64 v[32:33], 6, v[36:37]
	v_lshl_add_u64 v[32:33], v[134:135], 0, v[32:33]
	global_load_dwordx4 v[32:35], v[32:33], off
	s_waitcnt vmcnt(0)
	v_add_f32_e32 v32, v32, v33
	v_add_f32_e32 v33, v34, v35
	v_add_f32_e32 v32, v32, v33
	v_mov_b32_e32 v33, v32
	s_nop 1
	v_permlane16_swap_b32_e32 v32, v33
	v_add_f32_e32 v32, v32, v33
	v_mov_b32_e32 v33, v32
	s_nop 1
	v_permlane32_swap_b32_e32 v32, v33
	v_add_f32_e32 v32, v32, v33
	v_fmamk_f32 v32, v32, 0x3a800000, v206
	v_rsq_f32_e32 v32, v32
	s_nop 0
	v_mul_f32_e32 v32, s100, v32
	v_lshlrev_b64 v[34:35], 13, v[36:37]
	v_lshl_add_u64 v[34:35], s[60:61], 0, v[34:35]
	v_lshl_add_u64 v[34:35], v[34:35], 0, v[140:141]
	v_pk_mul_f32 v[30:31], v[30:31], v[32:33] op_sel_hi:[1,0]
	v_pk_mul_f32 v[28:29], v[28:29], v[32:33] op_sel_hi:[1,0]
	v_pk_mul_f32 v[36:37], v[26:27], v[32:33] op_sel_hi:[1,0]
	v_pk_mul_f32 v[26:27], v[24:25], v[32:33] op_sel_hi:[1,0]
	v_cvt_pk_bf16_f32 v24, v28, v29
	v_cvt_pk_bf16_f32 v25, v30, v31
	v_cvt_pk_bf16_f32 v26, v26, v27
	v_cvt_pk_bf16_f32 v27, v36, v37
	v_pk_mul_f32 v[20:21], v[20:21], v[32:33] op_sel_hi:[1,0]
	global_store_dwordx4 v[34:35], v[24:27], off
	v_pk_mul_f32 v[22:23], v[22:23], v[32:33] op_sel_hi:[1,0]
	s_nop 0
	v_pk_mul_f32 v[24:25], v[18:19], v[32:33] op_sel_hi:[1,0]
	v_pk_mul_f32 v[18:19], v[16:17], v[32:33] op_sel_hi:[1,0]
	v_cvt_pk_bf16_f32 v16, v20, v21
	v_add_u32_e32 v20, 0xb0, v142
	v_cvt_pk_bf16_f32 v17, v22, v23
	v_cvt_pk_bf16_f32 v18, v18, v19
	v_cvt_pk_bf16_f32 v19, v24, v25
	v_ashrrev_i32_e32 v21, 31, v20
	global_store_dwordx4 v[34:35], v[16:19], off offset:256
	s_nop 1
	v_lshlrev_b64 v[16:17], 6, v[20:21]
	v_lshl_add_u64 v[16:17], v[134:135], 0, v[16:17]
	global_load_dwordx4 v[16:19], v[16:17], off
	s_waitcnt vmcnt(0)
	v_add_f32_e32 v16, v16, v17
	v_add_f32_e32 v17, v18, v19
	v_add_f32_e32 v16, v16, v17
	v_mov_b32_e32 v17, v16
	s_nop 1
	v_permlane16_swap_b32_e32 v16, v17
	v_add_f32_e32 v16, v16, v17
	v_mov_b32_e32 v17, v16
	s_nop 1
	v_permlane32_swap_b32_e32 v16, v17
	v_add_f32_e32 v16, v16, v17
	v_fmamk_f32 v16, v16, 0x3a800000, v206
	v_rsq_f32_e32 v16, v16
	s_nop 0
	v_mul_f32_e32 v16, s100, v16
	v_lshlrev_b64 v[18:19], 13, v[20:21]
	v_lshl_add_u64 v[18:19], s[60:61], 0, v[18:19]
	v_lshl_add_u64 v[18:19], v[18:19], 0, v[140:141]
	v_pk_mul_f32 v[14:15], v[14:15], v[16:17] op_sel_hi:[1,0]
	v_pk_mul_f32 v[12:13], v[12:13], v[16:17] op_sel_hi:[1,0]
	v_pk_mul_f32 v[20:21], v[10:11], v[16:17] op_sel_hi:[1,0]
	v_pk_mul_f32 v[10:11], v[8:9], v[16:17] op_sel_hi:[1,0]
	v_cvt_pk_bf16_f32 v8, v12, v13
	v_cvt_pk_bf16_f32 v9, v14, v15
	v_cvt_pk_bf16_f32 v10, v10, v11
	v_cvt_pk_bf16_f32 v11, v20, v21
	global_store_dwordx4 v[18:19], v[8:11], off
	v_pk_mul_f32 v[6:7], v[6:7], v[16:17] op_sel_hi:[1,0]
	v_pk_mul_f32 v[4:5], v[4:5], v[16:17] op_sel_hi:[1,0]
	v_pk_mul_f32 v[8:9], v[2:3], v[16:17] op_sel_hi:[1,0]
	v_pk_mul_f32 v[2:3], v[0:1], v[16:17] op_sel_hi:[1,0]
	v_cvt_pk_bf16_f32 v0, v4, v5
	v_cvt_pk_bf16_f32 v1, v6, v7
	v_cvt_pk_bf16_f32 v2, v2, v3
	v_cvt_pk_bf16_f32 v3, v8, v9
	global_store_dwordx4 v[18:19], v[0:3], off offset:256
	s_cbranch_vccnz .LBB0_76
	s_andn2_b64 vcc, exec, s[38:39]
	s_cbranch_vccnz .LBB0_75
	s_barrier
	s_branch .LBB0_75

; __global__ void __launch_bounds__(512, 2) fwd_megakernel(Args a) {
;     ...
;             int lz = l, lanez = threadIdx.x; asm volatile("" : "+s"(lz), "+v"(lanez)); lanez &= 63;
;             const float li = 0.8f - 0.6f * expf(-0.3f * (float)lz);
;             const float p1 = wave_sum(a.lq1[lz * 64 + lanez] * a.lk1[lz * 64 + lanez]), p2 = wave_sum(a.lq2[lz * 64 + lanez] * a.lk2[lz * 64 + lanez]);
;             const float lam = __uint_as_float(__builtin_amdgcn_readfirstlane(__float_as_uint(expf(p1) - expf(p2) + li)));
;             const int vcuz = vcu + (lz - l);
;             for (int u = vcuz; u < 2048; u += G) att::da_unit(lds, proj, yb, u, a.t5, lam, __uint_as_float(__builtin_amdgcn_readfirstlane(__float_as_uint(1.0f - li))), a.subg + lz * 128);
;             for (int u = vcuz; u < 2048; u += G) att::na_unit(lds, proj, yb, u, a.rpb + (size_t)lz * 8 * 465);
.LBB0_147:
	s_andn2_b64 vcc, exec, s[30:31]
	s_cbranch_vccnz .LBB0_295
	s_mov_b32 s74, s71
	v_mov_b32_e32 v0, v204
	s_mov_b32 s0, 0x3fb8aa3b
	v_cvt_f32_i32_e32 v1, s74
	s_mov_b32 s1, 0xc2ce8ed0
	s_mov_b32 s4, 0x42b17218
	v_and_b32_e32 v0, 63, v0
	v_mul_f32_e32 v1, 0xbe99999a, v1
	v_mul_f32_e32 v2, 0x3fb8aa3b, v1
	v_fma_f32 v3, v1, s0, -v2
	v_rndne_f32_e32 v4, v2
	v_fmac_f32_e32 v3, 0x32a5705f, v1
	v_sub_f32_e32 v2, v2, v4
	v_add_f32_e32 v2, v2, v3
	v_exp_f32_e32 v2, v2
	v_cvt_i32_f32_e32 v3, v4
	v_cmp_ngt_f32_e32 vcc, s1, v1
	v_lshl_or_b32 v0, s74, 6, v0
	v_readlane_b32 s76, v249, 5
	v_ldexp_f32 v2, v2, v3
	v_cndmask_b32_e32 v2, 0, v2, vcc
	v_cmp_nlt_f32_e32 vcc, s4, v1
	v_readlane_b32 s80, v249, 9
	v_readlane_b32 s81, v249, 10
	v_cndmask_b32_e32 v1, v210, v2, vcc
	v_fmamk_f32 v222, v1, 0xbf19999a, v208
	v_ashrrev_i32_e32 v1, 31, v0
	v_readlane_b32 s82, v249, 11
	v_readlane_b32 s83, v249, 12
	v_readlane_b32 s84, v249, 13
	v_readlane_b32 s85, v249, 14
	v_readlane_b32 s86, v249, 15
	v_readlane_b32 s87, v249, 16
	v_lshlrev_b64 v[0:1], 2, v[0:1]
	v_readlane_b32 s88, v249, 17
	v_readlane_b32 s89, v249, 18
	v_readlane_b32 s90, v249, 19
	v_readlane_b32 s91, v249, 20
	s_mov_b64 s[80:81], s[84:85]
	s_mov_b64 s[82:83], s[86:87]
	v_lshl_add_u64 v[2:3], s[80:81], 0, v[0:1]
	global_load_dword v4, v[2:3], off
	v_lshl_add_u64 v[2:3], s[82:83], 0, v[0:1]
	global_load_dword v2, v[2:3], off
	v_and_b32_e32 v5, 64, v205
	v_add_u32_e32 v5, 64, v5
	v_xor_b32_e32 v6, 1, v205
	v_cmp_lt_i32_e32 vcc, v6, v5
	s_mov_b64 s[84:85], s[88:89]
	s_mov_b64 s[86:87], s[90:91]
	v_cndmask_b32_e32 v6, v205, v6, vcc
	v_lshlrev_b32_e32 v6, 2, v6
	s_mov_b32 s12, s13
	v_readlane_b32 s77, v249, 6
	v_readlane_b32 s78, v249, 7
	v_readlane_b32 s79, v249, 8
	s_waitcnt vmcnt(0)
	v_mul_f32_e32 v3, v4, v2
	ds_bpermute_b32 v3, v6, v3
	s_waitcnt lgkmcnt(0)
	v_fmac_f32_e32 v3, v4, v2
	v_xor_b32_e32 v2, 2, v205
	v_cmp_lt_i32_e32 vcc, v2, v5
	s_nop 1
	v_cndmask_b32_e32 v2, v205, v2, vcc
	v_lshlrev_b32_e32 v4, 2, v2
	ds_bpermute_b32 v2, v4, v3
	s_waitcnt lgkmcnt(0)
	v_add_f32_e32 v2, v3, v2
	v_xor_b32_e32 v3, 4, v205
	v_cmp_lt_i32_e32 vcc, v3, v5
	s_nop 1
	v_cndmask_b32_e32 v3, v205, v3, vcc
	v_lshlrev_b32_e32 v7, 2, v3
	ds_bpermute_b32 v3, v7, v2
	s_waitcnt lgkmcnt(0)
	v_add_f32_e32 v2, v2, v3
	v_xor_b32_e32 v3, 8, v205
	v_cmp_lt_i32_e32 vcc, v3, v5
	s_nop 1
	v_cndmask_b32_e32 v3, v205, v3, vcc
	v_lshlrev_b32_e32 v8, 2, v3
	ds_bpermute_b32 v3, v8, v2
	s_waitcnt lgkmcnt(0)
	v_add_f32_e32 v2, v2, v3
	v_xor_b32_e32 v3, 16, v205
	v_cmp_lt_i32_e32 vcc, v3, v5
	s_nop 1
	v_cndmask_b32_e32 v3, v205, v3, vcc
	v_lshlrev_b32_e32 v9, 2, v3
	ds_bpermute_b32 v3, v9, v2
	s_waitcnt lgkmcnt(0)
	v_add_f32_e32 v2, v2, v3
	v_xor_b32_e32 v3, 32, v205
	v_cmp_lt_i32_e32 vcc, v3, v5
	s_nop 1
	v_cndmask_b32_e32 v3, v205, v3, vcc
	v_lshlrev_b32_e32 v5, 2, v3
	ds_bpermute_b32 v3, v5, v2
	s_waitcnt lgkmcnt(0)
	v_add_f32_e32 v10, v2, v3
	v_lshl_add_u64 v[2:3], s[84:85], 0, v[0:1]
	v_lshl_add_u64 v[0:1], s[86:87], 0, v[0:1]
	global_load_dword v2, v[2:3], off
	v_cmp_ngt_f32_e32 vcc, s1, v10
	global_load_dword v0, v[0:1], off
	s_waitcnt vmcnt(0)
	v_mul_f32_e32 v1, v2, v0
	ds_bpermute_b32 v1, v6, v1
	s_waitcnt lgkmcnt(0)
	v_fmac_f32_e32 v1, v2, v0
	ds_bpermute_b32 v0, v4, v1
	s_waitcnt lgkmcnt(0)
	v_add_f32_e32 v0, v1, v0
	ds_bpermute_b32 v1, v7, v0
	s_waitcnt lgkmcnt(0)
	v_add_f32_e32 v0, v0, v1
	ds_bpermute_b32 v1, v8, v0
	s_waitcnt lgkmcnt(0)
	v_add_f32_e32 v0, v0, v1
	ds_bpermute_b32 v1, v9, v0
	s_waitcnt lgkmcnt(0)
	v_add_f32_e32 v0, v0, v1
	ds_bpermute_b32 v1, v5, v0
	s_waitcnt lgkmcnt(0)
	v_add_f32_e32 v0, v0, v1
	v_mul_f32_e32 v1, 0x3fb8aa3b, v10
	v_fma_f32 v2, v10, s0, -v1
	v_rndne_f32_e32 v3, v1
	v_fmac_f32_e32 v2, 0x32a5705f, v10
	v_sub_f32_e32 v1, v1, v3
	v_add_f32_e32 v1, v1, v2
	v_exp_f32_e32 v1, v1
	v_cvt_i32_f32_e32 v2, v3
	v_ldexp_f32 v1, v1, v2
	v_mul_f32_e32 v2, 0x3fb8aa3b, v0
	v_fma_f32 v3, v0, s0, -v2
	v_rndne_f32_e32 v4, v2
	v_fmac_f32_e32 v3, 0x32a5705f, v0
	v_sub_f32_e32 v2, v2, v4
	v_add_f32_e32 v2, v2, v3
	v_exp_f32_e32 v2, v2
	v_cvt_i32_f32_e32 v3, v4
	v_cndmask_b32_e32 v1, 0, v1, vcc
	v_cmp_nlt_f32_e32 vcc, s4, v10
	s_sub_i32 s0, s74, s71
	v_ldexp_f32 v2, v2, v3
	v_cndmask_b32_e32 v1, v210, v1, vcc
	v_cmp_ngt_f32_e32 vcc, s1, v0
	v_readlane_b32 s1, v249, 2
	s_add_i32 s96, s0, s1
	v_cndmask_b32_e32 v2, 0, v2, vcc
	v_cmp_nlt_f32_e32 vcc, s4, v0
	s_cmpk_gt_i32 s96, 0x7ff
	s_nop 0
	v_cndmask_b32_e32 v0, v210, v2, vcc
	v_sub_f32_e32 v0, v1, v0
	v_add_f32_e32 v0, v222, v0
	s_nop 0
	v_readfirstlane_b32 s75, v0
	s_cbranch_scc1 .LBB0_241
	s_lshl_b32 s0, s74, 7
	s_ashr_i32 s1, s0, 31
	s_lshl_b64 s[0:1], s[0:1], 2
	s_add_u32 s38, s44, s0
	s_addc_u32 s39, s45, s1
	s_add_i32 s12, s74, s70
	s_lshl_b32 s72, s12, 7
	s_mov_b32 s73, s96
	v_lshlrev_b32_e32 v255, 4, v204
	v_add_u32_e32 v255, 0x1b000, v255
	ds_write_b128 v255, v[156:159]
	ds_write_b128 v255, v[160:163] offset:8192
	ds_write_b128 v255, v[214:217] offset:20736
	ds_write_b128 v255, v[218:221] offset:28928
	s_waitcnt lgkmcnt(0)
	s_branch .LBB0_151

; #define LAS __attribute__((address_space(3)))
; __device__ __forceinline__ int vpos_of(int c) { const int c16 = c & 15; return (c & ~15) + 8 * ((c16 >> 2) & 1) + (c16 & 3) + 4 * (c16 >> 3); }
; __device__ __forceinline__ void da_unit(LAS unsigned char* lds, const bf16_t* __restrict__ proj, bf16_t* __restrict__ y, int unit,
;                                         const float* __restrict__ t5, float lam, float one_m_li, const float* __restrict__ subg) {
;     ...
;     if (tid < 257) { const int rel = tid - 128, a = rel < 0 ? -rel : rel; int large = 8 + (31 - __builtin_clz((unsigned)(a * a) | 1u)) - 6; large = large > 15 ? 15 : large;
;         const int bucket = (rel > 0 ? 16 : 0) + (a < 8 ? a : large); tbl[tid] = t5[bucket * 4 + h] * LOG2E; }
;     LAS float* sgt = (LAS float*)(lds + DA_TBL_OFF + 2048);
;     if (tid >= 384) sgt[tid - 384] = subg[tid - 384];
;     { const float bl_ = t5[15 * 4 + h], br_ = t5[31 * 4 + h];
; #pragma unroll
;       for (int k_ = 0; k_ < 3; ++k_) { const int e_ = tid + 512 * k_;
;           if (e_ < 2 * 641) { const int side = e_ >= 641 ? 1 : 0, rel0 = e_ - 641 * side - 320, rel = clampi(rel0, -128, 128), a = rel < 0 ? -rel : rel;
;               int large = 8 + (31 - __builtin_clz((unsigned)(a * a) | 1u)) - 6; large = large > 15 ? 15 : large;
;               const int bucket = (rel > 0 ? 16 : 0) + (a < 8 ? a : large);
;               ((LAS float*)(lds + DA_DL_OFF))[e_ + (side ? (DA_DR_OFF - DA_DL_OFF) / 4 - 641 : 0)] = (t5[bucket * 4 + h] - (side ? br_ : bl_)) * (LOG2E / QK_C); } } }
;     float tbmax = t5[l31 * 4 + h] * LOG2E;
; #pragma unroll
;     for (int o_ = 1; o_ < 32; o_ <<= 1) tbmax = fmaxf(tbmax, __shfl_xor(tbmax, o_));
;     const bf16_t* qp = proj + (rowbase + q) * 4096 + 2048 + h * 128 + mp * 64 + hh * 8;
;     bf16x8 qf[4];
; #pragma unroll
;     for (int ks = 0; ks < 4; ++ks) qf[ks] = *(const bf16x8*)(qp + ks * 16);
;     const int kc = tid & 15, kr = tid >> 4;
;     const bf16_t* kvbase = proj + rowbase * 4096 + 2560 + h * 128;
;     const unsigned kgo = (unsigned)(kr * 4096 + kc * 8), vgo = (unsigned)(2 * kr * 4096 + 512 + kc * 8);
;     const int vps = vpos_of(2 * kr), vch = vps >> 3, vswc = vsw(8 * kc);
;     const unsigned kw = kr * DA_KROW + kc * 16, vwb = DA_V_OFF + (8 * kc) * DA_VROW + ((vps & 7) >> 1) * 4;
;     const unsigned vwA = vwb + ((vch ^ vswc) << 4), vwB = vwb + ((vch ^ vswc ^ 4) << 4);
.LBB0_155:
	s_or_b64 exec, exec, s[30:31]
	s_lshl_b32 s4, s9, 2
	v_mov_b32_e32 v2, s4
	global_load_dword v1, v2, s[46:47] offset:240
	s_nop 0
	global_load_dword v2, v2, s[46:47] offset:496
	s_movk_i32 s4, 0x502
	v_cmp_gt_i32_e32 vcc, s4, v0
	s_and_saveexec_b64 s[30:31], vcc
	s_cbranch_execz .LBB0_157
	s_movk_i32 s4, 0x280
	v_cmp_lt_i32_e32 vcc, s4, v0
	s_nop 1
	v_cndmask_b32_e32 v3, 0, v211, vcc
	v_add_u32_e32 v3, v3, v0
	v_med3_i32 v4, v3, s34, v212
	v_add_u32_e32 v4, 0xfffffec0, v4
	v_sub_u32_e32 v5, 0, v4
	v_max_i32_e32 v5, v4, v5
	v_mul_i32_i24_e32 v4, v4, v4
	v_or_b32_e32 v4, 1, v4
	v_ffbh_u32_e32 v4, v4
	v_sub_u32_e32 v4, 33, v4
	v_cmp_lt_i32_e64 s[36:37], s64, v3
	v_min_u32_e32 v4, 15, v4
	s_nop 0
	v_cndmask_b32_e64 v3, 0, 16, s[36:37]
	v_cmp_gt_u32_e64 s[36:37], 8, v5
	s_nop 1
	v_cndmask_b32_e64 v4, v4, v5, s[36:37]
	v_add_u32_e32 v3, v4, v3
	v_lshl_or_b32 v152, v3, 2, s9
	v_lshl_add_u64 v[4:5], v[152:153], 2, s[46:47]
	global_load_dword v3, v[4:5], off
	s_waitcnt vmcnt(1)
	v_cndmask_b32_e32 v4, v1, v2, vcc
	v_lshlrev_b32_e32 v5, 2, v0
	s_waitcnt vmcnt(0)
	v_sub_f32_e32 v3, v3, v4
	v_cndmask_b32_e32 v4, 0, v213, vcc
	v_mul_f32_e32 v3, 0x3fb8aa3b, v3
	v_add3_u32 v4, s65, v5, v4
	ds_write_b32 v4, v3
.LBB0_157:
	s_or_b64 exec, exec, s[30:31]
	s_movk_i32 s4, 0x302
	v_cmp_gt_i32_e32 vcc, s4, v0
	s_and_saveexec_b64 s[30:31], vcc
	s_cbranch_execz .LBB0_159
	v_cmp_lt_i32_e32 vcc, s35, v0
	v_add_u32_e32 v3, 0x200, v0
	s_nop 0
	v_cndmask_b32_e32 v4, 0, v211, vcc
	v_add_u32_e32 v4, v4, v3
	v_med3_i32 v5, v4, s34, v212
	v_add_u32_e32 v5, 0xfffffec0, v5
	v_sub_u32_e32 v6, 0, v5
	v_max_i32_e32 v6, v5, v6
	v_mul_i32_i24_e32 v5, v5, v5
	v_or_b32_e32 v5, 1, v5
	v_ffbh_u32_e32 v5, v5
	v_sub_u32_e32 v5, 33, v5
	v_cmp_lt_i32_e64 s[36:37], s64, v4
	v_min_u32_e32 v5, 15, v5
	v_lshlrev_b32_e32 v3, 2, v3
	v_cndmask_b32_e64 v4, 0, 16, s[36:37]
	v_cmp_gt_u32_e64 s[36:37], 8, v6
	s_nop 1
	v_cndmask_b32_e64 v5, v5, v6, s[36:37]
	v_add_u32_e32 v4, v5, v4
	v_lshl_or_b32 v152, v4, 2, s9
	v_lshl_add_u64 v[4:5], v[152:153], 2, s[46:47]
	global_load_dword v4, v[4:5], off
	s_waitcnt vmcnt(1)
	v_cndmask_b32_e32 v5, v1, v2, vcc
	v_cndmask_b32_e32 v6, 0, v213, vcc
	v_add3_u32 v3, s65, v6, v3
	s_waitcnt vmcnt(0)
	v_sub_f32_e32 v4, v4, v5
	v_mul_f32_e32 v4, 0x3fb8aa3b, v4
	ds_write_b32 v3, v4
.LBB0_159:
	s_or_b64 exec, exec, s[30:31]
	s_movk_i32 s4, 0x102
	v_cmp_gt_i32_e32 vcc, s4, v0
	s_and_saveexec_b64 s[30:31], vcc
	s_cbranch_execz .LBB0_161
	s_movk_i32 s4, 0xfe80
	v_cmp_lt_i32_e32 vcc, s4, v0
	v_add_u32_e32 v3, 0x400, v0
	s_nop 0
	v_cndmask_b32_e32 v4, 0, v211, vcc
	v_add_u32_e32 v4, v4, v3
	v_med3_i32 v5, v4, s34, v212
	v_add_u32_e32 v5, 0xfffffec0, v5
	v_sub_u32_e32 v6, 0, v5
	v_max_i32_e32 v6, v5, v6
	v_mul_i32_i24_e32 v5, v5, v5
	v_or_b32_e32 v5, 1, v5
	v_ffbh_u32_e32 v5, v5
	v_sub_u32_e32 v5, 33, v5
	v_cmp_lt_i32_e64 s[36:37], s64, v4
	v_min_u32_e32 v5, 15, v5
	s_waitcnt vmcnt(0)
	v_cndmask_b32_e32 v1, v1, v2, vcc
	v_cndmask_b32_e64 v4, 0, 16, s[36:37]
	v_cmp_gt_u32_e64 s[36:37], 8, v6
	v_cndmask_b32_e32 v2, 0, v213, vcc
	v_lshlrev_b32_e32 v3, 2, v3
	v_cndmask_b32_e64 v5, v5, v6, s[36:37]
	v_add_u32_e32 v4, v5, v4
	v_lshl_or_b32 v152, v4, 2, s9
	v_lshl_add_u64 v[4:5], v[152:153], 2, s[46:47]
	global_load_dword v4, v[4:5], off
	v_add3_u32 v2, s65, v2, v3
	s_waitcnt vmcnt(0)
	v_sub_f32_e32 v1, v4, v1
	v_mul_f32_e32 v1, 0x3fb8aa3b, v1
	ds_write_b32 v2, v1
.LBB0_161:
	s_or_b64 exec, exec, s[30:31]
	s_ashr_i32 s30, s73, 7
	s_lshl_b32 s4, s73, 7
	s_ashr_i32 s7, s1, 2
	s_bfe_u32 s5, s1, 0x10006
	s_ashr_i32 s31, s30, 31
	s_and_b32 s97, s4, 0xf80
	s_andn2_b32 s7, s7, 31
	s_and_b32 s6, s72, 0xf80
	s_lshl_b64 s[76:77], s[30:31], 12
	s_add_i32 s8, s7, s97
	s_lshl_b32 s4, s9, 7
	s_lshl_b32 s40, s9, 8
	s_lshl_b32 s36, s5, 7
	s_lshl_b64 s[30:31], s[30:31], 25
	s_add_u32 s9, s60, s30
	s_waitcnt vmcnt(1)
	v_and_b32_e32 v1, 15, v0
	s_addc_u32 s10, s61, s31
	v_ashrrev_i32_e32 v46, 4, v0
	s_add_u32 s9, s9, s40
	s_waitcnt vmcnt(0)
	v_lshlrev_b32_e32 v2, 3, v1
	s_addc_u32 s10, s10, 0
	v_lshl_or_b32 v152, v46, 12, v2
	s_add_u32 s30, s9, 0x1400
	v_lshl_or_b32 v18, v46, 13, v2
	v_add_u32_e32 v168, 0x20000, v152
	v_mov_b32_e32 v169, v153
	s_addc_u32 s31, s10, 0
	v_lshlrev_b64 v[34:35], 1, v[152:153]
	v_lshlrev_b32_e32 v254, 1, v152
	v_lshlrev_b64 v[36:37], 1, v[168:169]
	v_lshlrev_b32_e32 v169, 1, v168
	v_or_b32_e32 v170, 0x1200, v18
	v_mov_b32_e32 v171, v153
	v_lshl_add_u64 v[2:3], s[30:31], 0, v[34:35]
	v_lshl_add_u64 v[6:7], s[30:31], 0, v[36:37]
	v_mov_b32_e32 v19, v153
	v_lshlrev_b64 v[38:39], 1, v[170:171]
	v_lshlrev_b32_e32 v171, 1, v170
	global_load_dwordx4 v[2:5], v[2:3], off
	s_nop 0
	global_load_dwordx4 v[6:9], v[6:7], off
	v_lshl_add_u64 v[10:11], v[18:19], 1, s[30:31]
	v_lshl_add_u64 v[14:15], s[30:31], 0, v[38:39]
	global_load_dwordx4 v[10:13], v[10:11], off offset:1024
	s_nop 0
	global_load_dwordx4 v[14:17], v[14:15], off
	v_or_b32_e32 v172, 0x200, v18
	v_mov_b32_e32 v173, v153
	s_add_u32 s78, s9, 0x81400
	s_addc_u32 s79, s10, 0
	v_lshlrev_b64 v[40:41], 1, v[172:173]
	v_lshlrev_b32_e32 v173, 1, v172
	v_lshl_add_u64 v[18:19], s[78:79], 0, v[34:35]
	v_lshl_add_u64 v[22:23], s[78:79], 0, v[36:37]
	v_lshl_add_u64 v[26:27], s[78:79], 0, v[40:41]
	v_lshl_add_u64 v[30:31], s[78:79], 0, v[38:39]
	global_load_dwordx4 v[18:21], v[18:19], off
	s_nop 0
	global_load_dwordx4 v[22:25], v[22:23], off
	s_nop 0
	global_load_dwordx4 v[26:29], v[26:27], off
	s_nop 0
	global_load_dwordx4 v[30:33], v[30:31], off
	v_and_b32_e32 v182, 31, v0
	v_or_b32_e32 v42, s8, v182
	v_ashrrev_i32_e32 v43, 31, v42
	v_lshl_add_u64 v[164:165], s[76:77], 0, v[42:43]
	v_lshlrev_b64 v[42:43], 13, v[164:165]
; __device__ __forceinline__ int vpos_of(int c) { const int c16 = c & 15; return (c & ~15) + 8 * ((c16 >> 2) & 1) + (c16 & 3) + 4 * (c16 >> 3); }
; __device__ __forceinline__ int vsw(int d) { return ((d >> 3) & 1) | (((d >> 4) & 1) << 1) | ((((d >> 1) ^ (d >> 5)) & 1) << 2); }
; __device__ __forceinline__ void da_unit(LAS unsigned char* lds, const bf16_t* __restrict__ proj, bf16_t* __restrict__ y, int unit,
;                                         const float* __restrict__ t5, float lam, float one_m_li, const float* __restrict__ subg) {
;     ...
;     const bf16_t* qp = proj + (rowbase + q) * 4096 + 2048 + h * 128 + mp * 64 + hh * 8;
;     bf16x8 qf[4];
; #pragma unroll
;     for (int ks = 0; ks < 4; ++ks) qf[ks] = *(const bf16x8*)(qp + ks * 16);
;     const int kc = tid & 15, kr = tid >> 4;
;     const bf16_t* kvbase = proj + rowbase * 4096 + 2560 + h * 128;
;     const unsigned kgo = (unsigned)(kr * 4096 + kc * 8), vgo = (unsigned)(2 * kr * 4096 + 512 + kc * 8);
;     const int vps = vpos_of(2 * kr), vch = vps >> 3, vswc = vsw(8 * kc);
;     const unsigned kw = kr * DA_KROW + kc * 16, vwb = DA_V_OFF + (8 * kc) * DA_VROW + ((vps & 7) >> 1) * 4;
;     const unsigned vwA = vwb + ((vch ^ vswc) << 4), vwB = vwb + ((vch ^ vswc ^ 4) << 4);
;     const unsigned vrd = (unsigned)(DA_V_OFF + l31 * DA_VROW) ^ (unsigned)((hh ^ vsw(l31)) << 4);
;     u32x4 kreg0, kreg1, vreg0, vreg1;
;     ...
;     f32x16 o[4];
; #pragma unroll
;     for (int t = 0; t < 4; ++t)
; #pragma unroll
;         for (int r = 0; r < 16; ++r) o[t][r] = 0.f;
;     float m = M_INIT, l = 0.f;
;     {
;       const u32x4 a0 = *(const u32x4*)(kvbase + kgo), a1 = *(const u32x4*)(kvbase + (kgo + 32u * 4096u)), a2 = *(const u32x4*)(kvbase + vgo), a3 = *(const u32x4*)(kvbase + (vgo + 4096u));
;       DA_LOAD(1);
;       const u32x4 b0 = kreg0, b1 = kreg1, b2 = vreg0, b3 = vreg1;
;       DA_LOAD(2);
;       const u32x4 c0 = kreg0, c1 = kreg1, c2 = vreg0, c3 = vreg1;
;       kreg0 = a0; kreg1 = a1; vreg0 = a2; vreg1 = a3; DA_STORE(lds);
;       kreg0 = b0; kreg1 = b1; vreg0 = b2; vreg1 = b3; DA_STORE(lds + DA_BUF);
;       kreg0 = c0; kreg1 = c1; vreg0 = c2; vreg1 = c3; }
;     __syncthreads();
	v_lshl_add_u64 v[166:167], s[60:61], 0, v[42:43]
	v_bfe_u32 v196, v0, 5, 1
	v_lshl_add_u64 v[42:43], v[166:167], 0, s[40:41]
	s_mov_b32 s37, s41
	v_lshl_add_u64 v[42:43], v[42:43], 0, s[36:37]
	v_lshlrev_b32_e32 v174, 4, v196
	v_mov_b32_e32 v175, v153
	v_lshl_add_u64 v[42:43], v[42:43], 0, v[174:175]
	s_mov_b64 s[76:77], 0x1000
	s_movk_i32 s11, 0x1000
	v_lshl_add_u64 v[44:45], v[42:43], 0, s[76:77]
	v_add_co_u32_e32 v42, vcc, s11, v42
	s_movk_i32 s11, 0x110
	s_nop 0
	v_addc_co_u32_e32 v43, vcc, 0, v43, vcc
	global_load_dwordx4 v[96:99], v[44:45], off offset:32
	global_load_dwordx4 v[100:103], v[44:45], off offset:64
	global_load_dwordx4 v[104:107], v[42:43], off
	global_load_dwordx4 v[108:111], v[44:45], off offset:96
	v_lshlrev_b32_e32 v42, 1, v46
	v_lshlrev_b32_e32 v43, 2, v46
	v_and_b32_e32 v42, -14, v42
	v_and_or_b32 v43, v43, 8, v42
	v_lshrrev_b32_e32 v43, 3, v43
	v_bitop3_b32 v43, v43, v0, 7 bitop3:0x78
	v_bfe_u32 v45, v0, 3, 2
	v_lshlrev_b32_e32 v0, 1, v0
	v_and_b32_e32 v0, 4, v0
	v_bitop3_b32 v0, v0, v196, v45 bitop3:0x36
	s_add_u32 s78, s9, 0x101400
	v_lshlrev_b32_e32 v0, 4, v0
	v_mul_lo_u32 v45, v46, s11
	s_addc_u32 s79, s10, 0
	v_lshlrev_b32_e32 v44, 10, v1
	v_lshl_add_u32 v175, v1, 4, v45
	v_lshl_or_b32 v45, v182, 7, v0
	v_lshl_add_u64 v[0:1], s[78:79], 0, v[34:35]
	v_lshl_add_u64 v[34:35], s[78:79], 0, v[36:37]
	global_load_dwordx4 v[116:119], v[0:1], off
	global_load_dwordx4 v[120:123], v[34:35], off
	v_lshl_add_u64 v[0:1], s[78:79], 0, v[40:41]
	v_lshl_add_u64 v[34:35], s[78:79], 0, v[38:39]
	global_load_dwordx4 v[112:115], v[0:1], off
	global_load_dwordx4 v[124:127], v[34:35], off
	v_and_or_b32 v42, v46, 4, v42
	v_lshlrev_b32_e32 v42, 1, v42
	v_lshlrev_b32_e32 v43, 4, v43
	v_and_or_b32 v1, v42, 12, v44
	v_add_u32_e32 v0, 0, v175
	v_add_u32_e32 v184, v1, v43
	s_waitcnt vmcnt(15)
	ds_write_b128 v0, v[2:5]
	s_waitcnt vmcnt(14)
	ds_write_b128 v0, v[6:9] offset:8704
	v_add_u32_e32 v2, 0, v184
	v_xad_u32 v185, v43, 64, v1
	s_waitcnt vmcnt(12)
	v_perm_b32 v3, v14, v10, s66
	v_perm_b32 v4, v14, v10, s67
	v_add_u32_e32 v5, 0x4400, v2
	v_add_u32_e32 v1, 0, v185
	ds_write2_b32 v5, v3, v4 offset1:32
	v_perm_b32 v3, v15, v11, s66
	v_perm_b32 v4, v15, v11, s67
	v_add_u32_e32 v6, 0x4400, v1
	ds_write2_b32 v6, v3, v4 offset0:64 offset1:96
	v_perm_b32 v3, v16, v12, s66
	v_perm_b32 v4, v16, v12, s67
	ds_write2_b32 v5, v3, v4 offset0:128 offset1:160
	v_perm_b32 v3, v17, v13, s66
	v_perm_b32 v4, v17, v13, s67
	ds_write2_b32 v6, v3, v4 offset0:192 offset1:224
	s_waitcnt vmcnt(11)
	ds_write_b128 v0, v[18:21] offset:33792
	s_waitcnt vmcnt(10)
	ds_write_b128 v0, v[22:25] offset:42496
	s_waitcnt vmcnt(8)
	v_perm_b32 v0, v30, v26, s66
	v_perm_b32 v3, v30, v26, s67
	v_add_u32_e32 v2, 0xc800, v2
	ds_write2_b32 v2, v0, v3 offset1:32
	v_perm_b32 v0, v31, v27, s66
	v_perm_b32 v3, v31, v27, s67
	v_add_u32_e32 v1, 0xc800, v1
	ds_write2_b32 v1, v0, v3 offset0:64 offset1:96
	v_perm_b32 v0, v32, v28, s66
	v_perm_b32 v3, v32, v28, s67
	v_mul_u32_u24_e32 v186, 0x110, v182
	s_add_i32 s9, s36, 0
	ds_write2_b32 v2, v0, v3 offset0:128 offset1:160
	v_perm_b32 v0, v33, v29, s66
	v_perm_b32 v2, v33, v29, s67
	v_add3_u32 v187, s9, v186, v174
	ds_write2_b32 v1, v0, v2 offset0:192 offset1:224
	s_waitcnt lgkmcnt(0)
	s_barrier
; #define DA_KLD(KF_, Bk, sub) do { const LAS unsigned char* kp_ = (Bk) + (32 * (sub) + l31) * DA_KROW + mp * 128 + hh * 16; \
;         _Pragma("unroll") for (int ks = 0; ks < 4; ++ks) KF_[ks] = *(const LAS bf16x8*)(kp_ + ks * 32); } while (0)
; #define DA_VLD(VF_, Bv, sub, s2_) do { const unsigned r_ = (unsigned)(uintptr_t)(Bv) + vrd; \
;         _Pragma("unroll") for (int dt = 0; dt < 4; ++dt) VF_[dt] = *(const LAS bf16x8*)(uintptr_t)((r_ ^ (unsigned)((4 * (sub) + 2 * (s2_)) ^ ((dt & 1) << 2)) << 4) + dt * 32 * DA_VROW); } while (0)
; #define DA_QKM(S_, KF_) do { { f32x16 z_; _Pragma("unroll") for (int r_ = 0; r_ < 16; ++r_) z_[r_] = 0.f; S_ = mfma32(KF_[0], qf[0], z_); } _Pragma("unroll") for (int ks = 1; ks < 4; ++ks) S_ = mfma32(KF_[ks], qf[ks], S_); } while (0)
; __device__ __forceinline__ float rowmax16(const f32x16& z) {
;     float a = fmaxf(fmaxf(z[0], z[1]), z[2]), b = fmaxf(fmaxf(z[3], z[4]), z[5]);
;     a = fmaxf(fmaxf(a, z[6]), z[7]); b = fmaxf(fmaxf(b, z[8]), z[9]); a = fmaxf(fmaxf(a, z[10]), z[11]); b = fmaxf(fmaxf(b, z[12]), z[13]); a = fmaxf(fmaxf(a, z[14]), z[15]);
;     return fmaxf(a, b);
; }
; __device__ __forceinline__ void da_unit(LAS unsigned char* lds, const bf16_t* __restrict__ proj, bf16_t* __restrict__ y, int unit,
;                                         const float* __restrict__ t5, float lam, float one_m_li, const float* __restrict__ subg) {
;     ...
;     f32x16 sa, sb;
;     bf16x8 kF[4], vF[4], vS[4];
;     u32x4 pp0 = {0u, 0u, 0u, 0u}, pp1 = {0u, 0u, 0u, 0u}, pc0, pc1;
;     int bcur = 0, bprev = 0, bnext = DA_BUF, bnn = 2 * DA_BUF;
;     bool near = (63 >= qblk - 128) && (0 <= qblk + 255); float bc = tbl[0];
;     int dtoff = DA_DL_OFF;
;     DA_KLD(kF, lds, 0); DA_QKM(sa, kF);
;     DA_VLD(vF, lds + bprev, 1, 0);
	ds_read_b128 v[0:3], v187
	s_waitcnt vmcnt(5) lgkmcnt(0)
	v_mfma_f32_32x32x16_bf16 v[64:79], v[0:3], v[104:107], 0
	s_add_i32 s9, 0, 0x18c00
	v_mov_b32_e32 v4, s9
	ds_read_b32 v177, v4
	ds_read_b128 v[4:7], v187 offset:32
	ds_read_b128 v[8:11], v187 offset:64
	ds_read_b128 v[12:15], v187 offset:96
	v_add_u32_e32 v188, 0x4400, v45
	s_mov_b32 s76, 0
	v_add_u32_e32 v183, 0, v188
	s_mov_b32 s77, s76
	s_waitcnt lgkmcnt(2)
	v_mfma_f32_32x32x16_bf16 v[64:79], v[4:7], v[96:99], v[64:79]
	v_xor_b32_e32 v0, 64, v183
	s_mov_b32 s78, s76
	s_mov_b32 s79, s76
	s_mov_b32 s80, s76
	s_mov_b32 s81, s76
	s_mov_b32 s82, s76
	s_mov_b32 s83, s76
	s_waitcnt lgkmcnt(1)
	v_mfma_f32_32x32x16_bf16 v[64:79], v[8:11], v[100:103], v[64:79]
	s_mov_b32 s84, s76
	s_mov_b32 s85, s76
	s_mov_b32 s86, s76
	s_mov_b32 s87, s76
	s_mov_b32 s88, s76
	s_mov_b32 s89, s76
	s_mov_b32 s90, s76
	s_waitcnt vmcnt(4) lgkmcnt(0)
	v_mfma_f32_32x32x16_bf16 v[64:79], v[12:15], v[108:111], v[64:79]
	s_mov_b32 s91, s76
	v_mov_b64_e32 v[48:49], s[76:77]
	ds_read_b128 v[140:143], v0
	ds_read_b128 v[132:135], v0 offset:8192
	ds_read_b128 v[136:139], v183 offset:4096
	ds_read_b128 v[128:131], v183 offset:12288
	v_mov_b64_e32 v[50:51], s[78:79]
	v_mov_b64_e32 v[52:53], s[80:81]
	v_mov_b64_e32 v[54:55], s[82:83]
	v_mov_b64_e32 v[56:57], s[84:85]
	v_mov_b64_e32 v[58:59], s[86:87]
	v_mov_b64_e32 v[60:61], s[88:89]
	v_mov_b64_e32 v[62:63], s[90:91]
	s_add_i32 s80, s6, s7
	v_or_b32_e32 v0, s80, v182
	v_lshlrev_b32_e32 v0, 2, v0
	v_sub_u32_e32 v0, v174, v0
	v_add_u32_e32 v189, 0, v0
	v_mov_b64_e32 v[32:33], v[48:49]
	v_mov_b64_e32 v[16:17], v[48:49]
	v_mov_b64_e32 v[0:1], v[48:49]
	s_mov_b32 s37, 1
	s_add_i32 s40, s8, 0x9e
	s_add_i32 s77, s8, 0x7e
	v_mov_b32_e32 v176, 0xf149f2ca
	s_mov_b32 s6, 0x19800
	s_mov_b32 s83, 0x10800
	s_mov_b32 s82, 0x8400
	v_mov_b32_e32 v178, 0
	s_movk_i32 s81, 0x80
	v_mov_b32_e32 v148, 0
	v_mov_b32_e32 v149, 0
	v_mov_b32_e32 v150, 0
	v_mov_b32_e32 v151, 0
	v_mov_b32_e32 v144, 0
	v_mov_b32_e32 v145, 0
	v_mov_b32_e32 v146, 0
	v_mov_b32_e32 v147, 0
	v_mov_b64_e32 v[34:35], v[50:51]
	v_mov_b64_e32 v[36:37], v[52:53]
	v_mov_b64_e32 v[38:39], v[54:55]
	v_mov_b64_e32 v[40:41], v[56:57]
	v_mov_b64_e32 v[42:43], v[58:59]
	v_mov_b64_e32 v[44:45], v[60:61]
	v_mov_b64_e32 v[46:47], v[62:63]
	v_mov_b64_e32 v[18:19], v[50:51]
	v_mov_b64_e32 v[20:21], v[52:53]
	v_mov_b64_e32 v[22:23], v[54:55]
	v_mov_b64_e32 v[24:25], v[56:57]
	v_mov_b64_e32 v[26:27], v[58:59]
	v_mov_b64_e32 v[28:29], v[60:61]
	v_mov_b64_e32 v[30:31], v[62:63]
	v_mov_b64_e32 v[2:3], v[50:51]
	v_mov_b64_e32 v[4:5], v[52:53]
	v_mov_b64_e32 v[6:7], v[54:55]
	v_mov_b64_e32 v[8:9], v[56:57]
	v_mov_b64_e32 v[10:11], v[58:59]
	v_mov_b64_e32 v[12:13], v[60:61]
	v_mov_b64_e32 v[14:15], v[62:63]
	s_mov_b32 s7, s76
	s_mov_b32 s8, s76
	v_max3_f32 v250, v64, v65, v66
	v_max3_f32 v251, v67, v68, v69
	v_max3_f32 v250, v250, v70, v71
	v_max3_f32 v251, v251, v72, v73
	v_max3_f32 v250, v250, v74, v75
	v_max3_f32 v251, v251, v76, v77
	v_max3_f32 v250, v250, v78, v79
	v_max_f32_e32 v250, v250, v251
	v_mov_b32_e32 v251, v250
	s_nop 1
	v_permlane32_swap_b32_e32 v250, v251
	v_max_f32_e32 v250, v250, v251
	v_sub_f32_e32 v64, v64, v250
	v_sub_f32_e32 v65, v65, v250
	v_sub_f32_e32 v66, v66, v250
	v_sub_f32_e32 v67, v67, v250
	v_sub_f32_e32 v68, v68, v250
	v_sub_f32_e32 v69, v69, v250
	v_sub_f32_e32 v70, v70, v250
	v_sub_f32_e32 v71, v71, v250
	v_sub_f32_e32 v72, v72, v250
	v_sub_f32_e32 v73, v73, v250
	v_sub_f32_e32 v74, v74, v250
	v_sub_f32_e32 v75, v75, v250
	v_sub_f32_e32 v76, v76, v250
	v_sub_f32_e32 v77, v77, v250
	v_sub_f32_e32 v78, v78, v250
	v_sub_f32_e32 v79, v79, v250
	v_sub_f32_e32 v232, 0, v250
	v_sub_f32_e32 v233, 0, v250
	v_sub_f32_e32 v234, 0, v250
	v_sub_f32_e32 v235, 0, v250
	v_sub_f32_e32 v236, 0, v250
	v_sub_f32_e32 v237, 0, v250
	v_sub_f32_e32 v238, 0, v250
	v_sub_f32_e32 v239, 0, v250
	v_sub_f32_e32 v240, 0, v250
	v_sub_f32_e32 v241, 0, v250
	v_sub_f32_e32 v242, 0, v250
	v_sub_f32_e32 v243, 0, v250
	v_sub_f32_e32 v244, 0, v250
	v_sub_f32_e32 v245, 0, v250
	v_sub_f32_e32 v246, 0, v250
	v_sub_f32_e32 v247, 0, v250

.LBB0_164:
	s_add_i32 s8, s8, 0
	v_add_u32_e32 v80, s8, v188
	v_xor_b32_e32 v84, 0x60, v80
	v_xor_b32_e32 v92, 32, v80
	ds_read_b128 v[80:83], v84
	ds_read_b128 v[84:87], v84 offset:8192
	ds_read_b128 v[88:91], v92 offset:4096
	ds_read_b128 v[92:95], v92 offset:12288
	s_waitcnt lgkmcnt(8)
	v_mfma_f32_32x32x16_bf16 v[48:63], v[140:143], v[148:151], v[48:63]
	v_exp_f32_e32 v156, v64
	v_exp_f32_e32 v157, v65
	s_waitcnt lgkmcnt(6)
	v_mfma_f32_32x32x16_bf16 v[32:47], v[136:139], v[148:151], v[32:47]
	v_exp_f32_e32 v158, v66
	v_exp_f32_e32 v159, v67
	v_mfma_f32_32x32x16_bf16 v[16:31], v[132:135], v[148:151], v[16:31]
	v_exp_f32_e32 v160, v68
	v_exp_f32_e32 v161, v69
	s_waitcnt lgkmcnt(5)
	v_mfma_f32_32x32x16_bf16 v[0:15], v[128:131], v[148:151], v[0:15]
	s_add_i32 s87, s82, 0
	s_add_i32 s8, s36, s87
	v_add3_u32 v128, s8, v186, v174
	ds_read_b128 v[148:151], v128 offset:8704
	ds_read_b128 v[192:195], v128 offset:8736
	ds_read_b128 v[198:201], v128 offset:8768
	ds_read_b128 v[224:227], v128 offset:8800
	v_exp_f32_e32 v162, v70
	v_exp_f32_e32 v163, v71
	s_waitcnt lgkmcnt(7)
	v_mfma_f32_32x32x16_bf16 v[48:63], v[80:83], v[144:147], v[48:63]
	v_add_u32_e32 v190, s87, v188
	v_xor_b32_e32 v191, 64, v190
	ds_read_b128 v[128:131], v190
	ds_read_b128 v[132:135], v191 offset:4096
	ds_read_b128 v[136:139], v190 offset:8192
	ds_read_b128 v[140:143], v191 offset:12288
	v_exp_f32_e32 v214, v72
	v_exp_f32_e32 v215, v73
	s_waitcnt lgkmcnt(9)
	v_mfma_f32_32x32x16_bf16 v[32:47], v[88:91], v[144:147], v[32:47]
	v_exp_f32_e32 v216, v74
	v_exp_f32_e32 v217, v75
	v_mfma_f32_32x32x16_bf16 v[16:31], v[84:87], v[144:147], v[16:31]
	v_exp_f32_e32 v218, v76
	v_exp_f32_e32 v219, v77
	s_waitcnt lgkmcnt(8)
	v_mfma_f32_32x32x16_bf16 v[0:15], v[92:95], v[144:147], v[0:15]
	v_exp_f32_e32 v220, v78
	v_exp_f32_e32 v221, v79
	s_waitcnt lgkmcnt(7)
	v_mfma_f32_32x32x16_bf16 v[80:95], v[148:151], v[104:107], v[232:247]
	v_add_f32_e32 v253, v157, v156
	v_add_f32_e32 v253, v158, v253
	v_add_f32_e32 v253, v159, v253
	v_cvt_pk_bf16_f32 v144, v156, v157
	v_cvt_pk_bf16_f32 v145, v158, v159
	s_waitcnt lgkmcnt(6)
	v_mfma_f32_32x32x16_bf16 v[80:95], v[192:195], v[96:99], v[80:95]
	v_add_f32_e32 v253, v160, v253
	v_add_f32_e32 v253, v161, v253
	v_add_f32_e32 v253, v162, v253
	v_add_f32_e32 v253, v163, v253
	v_cvt_pk_bf16_f32 v146, v160, v161
	v_cvt_pk_bf16_f32 v147, v162, v163
	s_waitcnt lgkmcnt(5)
	v_mfma_f32_32x32x16_bf16 v[80:95], v[198:201], v[100:103], v[80:95]
	v_add_f32_e32 v253, v214, v253
	v_add_f32_e32 v253, v215, v253
	v_add_f32_e32 v253, v216, v253
	v_add_f32_e32 v253, v217, v253
	v_cvt_pk_bf16_f32 v148, v214, v215
	v_cvt_pk_bf16_f32 v149, v216, v217
	s_waitcnt lgkmcnt(4)
	v_mfma_f32_32x32x16_bf16 v[80:95], v[224:227], v[108:111], v[80:95]
	v_add_f32_e32 v253, v218, v253
	v_add_f32_e32 v253, v219, v253
	v_add_f32_e32 v253, v220, v253
	v_add_f32_e32 v192, v221, v253
	v_cvt_pk_bf16_f32 v150, v218, v219
	v_cvt_pk_bf16_f32 v151, v220, v221
	v_cmp_ngt_f32_e32 vcc, s68, v192
	s_cbranch_vccz .LBB0_167
	v_max3_f32 v250, v64, v65, v66
	v_max3_f32 v251, v67, v68, v69
	v_max3_f32 v250, v250, v70, v71
	v_max3_f32 v251, v251, v72, v73
	v_max3_f32 v250, v250, v74, v75
	v_max3_f32 v251, v251, v76, v77
	v_max3_f32 v250, v250, v78, v79
	v_max_f32_e32 v250, v250, v251
	v_mov_b32_e32 v251, v250
	s_nop 1
	v_permlane32_swap_b32_e32 v250, v251
	v_max_f32_e32 v250, v250, v251
	v_cmp_lt_f32_e32 vcc, v154, v250
	s_cbranch_vccz .LBB0_167
	s_nop 1
	v_cndmask_b32_e32 v250, 0, v250, vcc
	v_sub_f32_e32 v251, 0, v250
	v_exp_f32_e32 v251, v251
	s_nop 0
	v_mul_f32_e32 v0, v251, v0
	v_mul_f32_e32 v1, v251, v1
	v_mul_f32_e32 v2, v251, v2
	v_mul_f32_e32 v3, v251, v3
	v_mul_f32_e32 v4, v251, v4
	v_mul_f32_e32 v5, v251, v5
	v_mul_f32_e32 v6, v251, v6
	v_mul_f32_e32 v7, v251, v7
	v_mul_f32_e32 v8, v251, v8
	v_mul_f32_e32 v9, v251, v9
	v_mul_f32_e32 v10, v251, v10
	v_mul_f32_e32 v11, v251, v11
	v_mul_f32_e32 v12, v251, v12
	v_mul_f32_e32 v13, v251, v13
	v_mul_f32_e32 v14, v251, v14
	v_mul_f32_e32 v15, v251, v15
	v_mul_f32_e32 v16, v251, v16
	v_mul_f32_e32 v17, v251, v17
	v_mul_f32_e32 v18, v251, v18
	v_mul_f32_e32 v19, v251, v19
	v_mul_f32_e32 v20, v251, v20
	v_mul_f32_e32 v21, v251, v21
	v_mul_f32_e32 v22, v251, v22
	v_mul_f32_e32 v23, v251, v23
	v_mul_f32_e32 v24, v251, v24
	v_mul_f32_e32 v25, v251, v25
	v_mul_f32_e32 v26, v251, v26
	v_mul_f32_e32 v27, v251, v27
	v_mul_f32_e32 v28, v251, v28
	v_mul_f32_e32 v29, v251, v29
	v_mul_f32_e32 v30, v251, v30
	v_mul_f32_e32 v31, v251, v31
	v_mul_f32_e32 v32, v251, v32
	v_mul_f32_e32 v33, v251, v33
	v_mul_f32_e32 v34, v251, v34
	v_mul_f32_e32 v35, v251, v35
	v_mul_f32_e32 v36, v251, v36
	v_mul_f32_e32 v37, v251, v37
	v_mul_f32_e32 v38, v251, v38
	v_mul_f32_e32 v39, v251, v39
	v_mul_f32_e32 v40, v251, v40
	v_mul_f32_e32 v41, v251, v41
	v_mul_f32_e32 v42, v251, v42
	v_mul_f32_e32 v43, v251, v43
	v_mul_f32_e32 v44, v251, v44
	v_mul_f32_e32 v45, v251, v45
	v_mul_f32_e32 v46, v251, v46
	v_mul_f32_e32 v47, v251, v47
	v_mul_f32_e32 v48, v251, v48
	v_mul_f32_e32 v49, v251, v49
	v_mul_f32_e32 v50, v251, v50
	v_mul_f32_e32 v51, v251, v51
	v_mul_f32_e32 v52, v251, v52
	v_mul_f32_e32 v53, v251, v53
	v_mul_f32_e32 v54, v251, v54
	v_mul_f32_e32 v55, v251, v55
	v_mul_f32_e32 v56, v251, v56
	v_mul_f32_e32 v57, v251, v57
	v_mul_f32_e32 v58, v251, v58
	v_mul_f32_e32 v59, v251, v59
	v_mul_f32_e32 v60, v251, v60
	v_mul_f32_e32 v61, v251, v61
	v_mul_f32_e32 v62, v251, v62
	v_mul_f32_e32 v63, v251, v63
	v_mul_f32_e32 v178, v251, v178
	v_sub_f32_e32 v64, v64, v250
	v_sub_f32_e32 v65, v65, v250
	v_sub_f32_e32 v66, v66, v250
	v_sub_f32_e32 v67, v67, v250
	v_sub_f32_e32 v68, v68, v250
; #define DA_LOAD(j) do { const bf16_t* t_ = kvbase + (size_t)(j) * 64 * 4096; kreg0 = *(const u32x4*)(t_ + kgo); kreg1 = *(const u32x4*)(t_ + (kgo + 32u * 4096u)); vreg0 = *(const u32x4*)(t_ + vgo); vreg1 = *(const u32x4*)(t_ + (vgo + 4096u)); } while (0)
; __device__ __forceinline__ void da_unit(LAS unsigned char* lds, const bf16_t* __restrict__ proj, bf16_t* __restrict__ y, int unit,
;                                         const float* __restrict__ t5, float lam, float one_m_li, const float* __restrict__ subg) {
;     ...
; #pragma unroll 2
;     for (int j = 0; j < 64; ++j) {
;         const int j1 = j + 1;
;         const bool near1 = (64 * j1 + 63 >= qblk - 128) && (64 * j1 <= qblk + 255);
;         const float bc1 = tbl[(64 * j1 > qblk) ? 256 : 0]; const int dtoff1 = (64 * j1 > qblk) ? DA_DR_OFF : DA_DL_OFF;
;         DA_STEP(sa, sb, pp0, pp1, pc0, pc1, lds + bprev, 1, lds + bcur, 1, j * 64, lds + bcur, 0);
;         __syncthreads();
;         DA_STORE(lds + bnn); { const int jl = j + 3 < 64 ? j + 3 : 63; DA_LOAD(jl); }
;         DA_STEP(sb, sa, pc0, pc1, pp0, pp1, lds + bcur, 0, lds + bnext, 0, j * 64 + 32, lds + bcur, 1);
	v_sub_f32_e32 v69, v69, v250
	v_sub_f32_e32 v70, v70, v250
	v_sub_f32_e32 v71, v71, v250
	v_sub_f32_e32 v72, v72, v250
	v_sub_f32_e32 v73, v73, v250
	v_sub_f32_e32 v74, v74, v250
	v_sub_f32_e32 v75, v75, v250
	v_sub_f32_e32 v76, v76, v250
	v_sub_f32_e32 v77, v77, v250
	v_sub_f32_e32 v78, v78, v250
	v_sub_f32_e32 v79, v79, v250
	v_sub_f32_e32 v80, v80, v250
	v_sub_f32_e32 v81, v81, v250
	v_sub_f32_e32 v82, v82, v250
	v_sub_f32_e32 v83, v83, v250
	v_sub_f32_e32 v84, v84, v250
	v_sub_f32_e32 v85, v85, v250
	v_sub_f32_e32 v86, v86, v250
	v_sub_f32_e32 v87, v87, v250
	v_sub_f32_e32 v88, v88, v250
	v_sub_f32_e32 v89, v89, v250
	v_sub_f32_e32 v90, v90, v250
	v_sub_f32_e32 v91, v91, v250
	v_sub_f32_e32 v92, v92, v250
	v_sub_f32_e32 v93, v93, v250
	v_sub_f32_e32 v94, v94, v250
	v_sub_f32_e32 v95, v95, v250
	v_sub_f32_e32 v232, v232, v250
	v_sub_f32_e32 v233, v233, v250
	v_sub_f32_e32 v234, v234, v250
	v_sub_f32_e32 v235, v235, v250
	v_sub_f32_e32 v236, v236, v250
	v_sub_f32_e32 v237, v237, v250
	v_sub_f32_e32 v238, v238, v250
	v_sub_f32_e32 v239, v239, v250
	v_sub_f32_e32 v240, v240, v250
	v_sub_f32_e32 v241, v241, v250
	v_sub_f32_e32 v242, v242, v250
	v_sub_f32_e32 v243, v243, v250
	v_sub_f32_e32 v244, v244, v250
	v_sub_f32_e32 v245, v245, v250
	v_sub_f32_e32 v246, v246, v250
	v_sub_f32_e32 v247, v247, v250
	v_exp_f32_e32 v156, v64
	v_exp_f32_e32 v157, v65
	v_exp_f32_e32 v158, v66
	v_exp_f32_e32 v159, v67
	v_exp_f32_e32 v160, v68
	v_exp_f32_e32 v161, v69
	v_exp_f32_e32 v162, v70
	v_exp_f32_e32 v163, v71
	v_exp_f32_e32 v214, v72
	v_exp_f32_e32 v215, v73
	v_exp_f32_e32 v216, v74
	v_exp_f32_e32 v217, v75
	v_exp_f32_e32 v218, v76
	v_exp_f32_e32 v219, v77
	v_exp_f32_e32 v220, v78
	v_exp_f32_e32 v221, v79
	s_nop 0
	v_add_f32_e32 v253, v157, v156
	v_add_f32_e32 v253, v158, v253
	v_add_f32_e32 v253, v159, v253
	v_add_f32_e32 v253, v160, v253
	v_add_f32_e32 v253, v161, v253
	v_add_f32_e32 v253, v162, v253
	v_add_f32_e32 v253, v163, v253
	v_add_f32_e32 v253, v214, v253
	v_add_f32_e32 v253, v215, v253
	v_add_f32_e32 v253, v216, v253
	v_add_f32_e32 v253, v217, v253
	v_add_f32_e32 v253, v218, v253
	v_add_f32_e32 v253, v219, v253
	v_add_f32_e32 v253, v220, v253
	v_add_f32_e32 v192, v221, v253
	v_cvt_pk_bf16_f32 v144, v156, v157
	v_cvt_pk_bf16_f32 v145, v158, v159
	v_cvt_pk_bf16_f32 v146, v160, v161
	v_cvt_pk_bf16_f32 v147, v162, v163
	v_cvt_pk_bf16_f32 v148, v214, v215
	v_cvt_pk_bf16_f32 v149, v216, v217
	v_cvt_pk_bf16_f32 v150, v218, v219
	v_cvt_pk_bf16_f32 v151, v220, v221
.LBB0_167:
	s_add_i32 s9, s83, 0
	s_add_i32 s8, s37, -1
	v_add_u32_e32 v64, s9, v175
	s_waitcnt lgkmcnt(0)
	s_barrier
	s_waitcnt vmcnt(3)
	ds_write_b128 v64, v[116:119]
	s_waitcnt vmcnt(2)
	ds_write_b128 v64, v[120:123] offset:8704
	v_add_u32_e32 v64, s9, v184
	s_min_u32 s8, s8, 60
	s_waitcnt vmcnt(0)
	v_perm_b32 v65, v124, v112, s66
	v_perm_b32 v66, v124, v112, s67
	v_add_u32_e32 v64, 0x4400, v64
	s_lshl_b32 s8, s8, 19
	ds_write2_b32 v64, v65, v66 offset1:32
	v_add_u32_e32 v65, s9, v185
	s_add_u32 s8, s30, s8
	v_perm_b32 v66, v125, v113, s66
	v_perm_b32 v67, v125, v113, s67
	v_add_u32_e32 v65, 0x4400, v65
	s_addc_u32 s9, s31, 0
	ds_write2_b32 v65, v66, v67 offset0:64 offset1:96
	v_perm_b32 v66, v126, v114, s66
	v_perm_b32 v67, v126, v114, s67
	s_add_u32 s8, s8, 0x180000
	ds_write2_b32 v64, v66, v67 offset0:128 offset1:160
	v_perm_b32 v64, v127, v115, s66
	v_perm_b32 v66, v127, v115, s67
	s_addc_u32 s9, s9, 0
	ds_write2_b32 v65, v64, v66 offset0:192 offset1:224
	global_load_dwordx4 v[116:119], v254, s[8:9]
	global_load_dwordx4 v[124:127], v169, s[8:9]
	global_load_dwordx4 v[112:115], v173, s[8:9]
	global_load_dwordx4 v[120:123], v171, s[8:9]
	v_cmp_neq_f32_e32 vcc, v177, v179
	s_cbranch_vccz .Lda_bcskip2
	s_nop 0
	v_sub_f32_e32 v250, v179, v177
	v_add_f32_e32 v232, v232, v250
	v_add_f32_e32 v233, v233, v250
	v_add_f32_e32 v234, v234, v250
	v_add_f32_e32 v235, v235, v250
	v_add_f32_e32 v236, v236, v250
	v_add_f32_e32 v237, v237, v250
	v_add_f32_e32 v238, v238, v250
	v_add_f32_e32 v239, v239, v250
	v_add_f32_e32 v240, v240, v250
	v_add_f32_e32 v241, v241, v250
	v_add_f32_e32 v242, v242, v250
	v_add_f32_e32 v243, v243, v250
	v_add_f32_e32 v244, v244, v250
	v_add_f32_e32 v245, v245, v250
	v_add_f32_e32 v246, v246, v250
	v_add_f32_e32 v247, v247, v250
.Lda_bcskip2:
	s_cmp_gt_i32 s7, s77
	s_cselect_b64 s[8:9], -1, 0
	s_sub_i32 s7, s86, 63
	s_cmpk_gt_i32 s7, 0x7f
	s_cselect_b64 s[88:89], -1, 0
	s_or_b64 s[8:9], s[8:9], s[88:89]
	s_and_b64 vcc, exec, s[8:9]
	s_cbranch_vccnz .LBB0_169
	s_addk_i32 s6, 0x500
	v_add_u32_e32 v78, s6, v189
	ds_read2_b32 v[64:65], v78 offset0:48 offset1:49
	ds_read2_b32 v[66:67], v78 offset0:50 offset1:51
	ds_read2_b32 v[68:69], v78 offset0:56 offset1:57
	ds_read2_b32 v[70:71], v78 offset0:58 offset1:59
	ds_read2_b32 v[72:73], v78 offset0:32 offset1:33
	ds_read2_b32 v[74:75], v78 offset0:34 offset1:35
	ds_read2_b32 v[76:77], v78 offset0:40 offset1:41
	ds_read2_b32 v[78:79], v78 offset0:42 offset1:43
	s_waitcnt lgkmcnt(4)
	v_pk_add_f32 v[94:95], v[94:95], v[70:71]
	v_pk_add_f32 v[92:93], v[92:93], v[68:69]
	v_pk_add_f32 v[90:91], v[90:91], v[66:67]
	v_pk_add_f32 v[88:89], v[88:89], v[64:65]
	s_waitcnt lgkmcnt(0)
	v_pk_add_f32 v[86:87], v[86:87], v[78:79]
	v_pk_add_f32 v[84:85], v[84:85], v[76:77]
	v_pk_add_f32 v[82:83], v[82:83], v[74:75]
	v_pk_add_f32 v[80:81], v[80:81], v[72:73]
.LBB0_169:
	v_add_f32_e32 v192, v192, v178
	v_xor_b32_e32 v155, 32, v190
	v_xor_b32_e32 v178, 0x60, v190
	ds_read_b128 v[64:67], v155
	ds_read_b128 v[68:71], v178 offset:4096
	ds_read_b128 v[72:75], v155 offset:8192
	ds_read_b128 v[76:79], v178 offset:12288
	v_mfma_f32_32x32x16_bf16 v[48:63], v[128:131], v[144:147], v[48:63]
	v_exp_f32_e32 v156, v80
	v_exp_f32_e32 v157, v81
	v_mfma_f32_32x32x16_bf16 v[32:47], v[132:135], v[144:147], v[32:47]
	v_exp_f32_e32 v158, v82
	v_exp_f32_e32 v159, v83
	v_mfma_f32_32x32x16_bf16 v[16:31], v[136:139], v[144:147], v[16:31]
	v_exp_f32_e32 v160, v84
	v_exp_f32_e32 v161, v85
	v_mfma_f32_32x32x16_bf16 v[0:15], v[140:143], v[144:147], v[0:15]
	v_add_u32_e32 v128, s84, v187
	ds_read_b128 v[144:147], v128
	ds_read_b128 v[198:201], v128 offset:32
	ds_read_b128 v[224:227], v128 offset:64
	ds_read_b128 v[228:231], v128 offset:96
	v_exp_f32_e32 v162, v86
	v_exp_f32_e32 v163, v87
	s_waitcnt lgkmcnt(7)
	v_mfma_f32_32x32x16_bf16 v[48:63], v[64:67], v[148:151], v[48:63]
	ds_read_b128 v[132:135], v191
	ds_read_b128 v[128:131], v190 offset:4096
	ds_read_b128 v[136:139], v191 offset:8192
	ds_read_b128 v[140:143], v190 offset:12288
	v_exp_f32_e32 v214, v88
	v_exp_f32_e32 v215, v89
	s_waitcnt lgkmcnt(10)
	v_mfma_f32_32x32x16_bf16 v[32:47], v[68:71], v[148:151], v[32:47]
	v_exp_f32_e32 v216, v90
	v_exp_f32_e32 v217, v91
	s_waitcnt lgkmcnt(9)
	v_mfma_f32_32x32x16_bf16 v[16:31], v[72:75], v[148:151], v[16:31]
	v_exp_f32_e32 v218, v92
	v_exp_f32_e32 v219, v93
	s_waitcnt lgkmcnt(8)
	v_mfma_f32_32x32x16_bf16 v[0:15], v[76:79], v[148:151], v[0:15]
	v_exp_f32_e32 v220, v94
	v_exp_f32_e32 v221, v95
	s_waitcnt lgkmcnt(7)
	v_mfma_f32_32x32x16_bf16 v[64:79], v[144:147], v[104:107], v[232:247]
	v_add_f32_e32 v253, v157, v156
	v_add_f32_e32 v253, v158, v253
	v_add_f32_e32 v253, v159, v253
	v_cvt_pk_bf16_f32 v148, v214, v215
	v_cvt_pk_bf16_f32 v149, v216, v217
	s_waitcnt lgkmcnt(6)
	v_mfma_f32_32x32x16_bf16 v[64:79], v[198:201], v[96:99], v[64:79]
	v_add_f32_e32 v253, v160, v253
	v_add_f32_e32 v253, v161, v253
	v_add_f32_e32 v253, v162, v253
	v_add_f32_e32 v253, v163, v253
	v_cvt_pk_bf16_f32 v150, v218, v219
	v_cvt_pk_bf16_f32 v151, v220, v221
	s_waitcnt lgkmcnt(5)
	v_mfma_f32_32x32x16_bf16 v[64:79], v[224:227], v[100:103], v[64:79]
	v_add_f32_e32 v253, v214, v253
	v_add_f32_e32 v253, v215, v253
	v_add_f32_e32 v253, v216, v253
	v_add_f32_e32 v253, v217, v253
	v_cvt_pk_bf16_f32 v144, v156, v157
	v_cvt_pk_bf16_f32 v145, v158, v159
	s_waitcnt lgkmcnt(4)
	v_mfma_f32_32x32x16_bf16 v[64:79], v[228:231], v[108:111], v[64:79]
	v_add_f32_e32 v253, v218, v253
	v_add_f32_e32 v253, v219, v253
	v_add_f32_e32 v253, v220, v253
	v_add_f32_e32 v190, v221, v253
	v_cvt_pk_bf16_f32 v146, v160, v161
	v_cvt_pk_bf16_f32 v147, v162, v163
	v_cmp_ngt_f32_e32 vcc, s68, v190
	s_cbranch_vccz .LBB0_172
	v_max3_f32 v250, v80, v81, v82
	v_max3_f32 v251, v83, v84, v85
	v_max3_f32 v250, v250, v86, v87
	v_max3_f32 v251, v251, v88, v89
	v_max3_f32 v250, v250, v90, v91
	v_max3_f32 v251, v251, v92, v93
	v_max3_f32 v250, v250, v94, v95
	v_max_f32_e32 v250, v250, v251
	v_mov_b32_e32 v251, v250
	s_nop 1
	v_permlane32_swap_b32_e32 v250, v251
	v_max_f32_e32 v250, v250, v251
	v_cmp_lt_f32_e32 vcc, v154, v250
	s_cbranch_vccz .LBB0_172
	s_nop 1
	v_cndmask_b32_e32 v250, 0, v250, vcc
	v_sub_f32_e32 v251, 0, v250
	v_exp_f32_e32 v251, v251
	s_nop 0
	v_mul_f32_e32 v0, v251, v0
	v_mul_f32_e32 v1, v251, v1
	v_mul_f32_e32 v2, v251, v2
	v_mul_f32_e32 v3, v251, v3
	v_mul_f32_e32 v4, v251, v4
	v_mul_f32_e32 v5, v251, v5
	v_mul_f32_e32 v6, v251, v6
	v_mul_f32_e32 v7, v251, v7
	v_mul_f32_e32 v8, v251, v8
	v_mul_f32_e32 v9, v251, v9
	v_mul_f32_e32 v10, v251, v10
	v_mul_f32_e32 v11, v251, v11
	v_mul_f32_e32 v12, v251, v12
	v_mul_f32_e32 v13, v251, v13
	v_mul_f32_e32 v14, v251, v14
	v_mul_f32_e32 v15, v251, v15
	v_mul_f32_e32 v16, v251, v16
	v_mul_f32_e32 v17, v251, v17
	v_mul_f32_e32 v18, v251, v18
	v_mul_f32_e32 v19, v251, v19
	v_mul_f32_e32 v20, v251, v20
	v_mul_f32_e32 v21, v251, v21
	v_mul_f32_e32 v22, v251, v22
	v_mul_f32_e32 v23, v251, v23
	v_mul_f32_e32 v24, v251, v24
	v_mul_f32_e32 v25, v251, v25
	v_mul_f32_e32 v26, v251, v26
	v_mul_f32_e32 v27, v251, v27
	v_mul_f32_e32 v28, v251, v28
	v_mul_f32_e32 v29, v251, v29
	v_mul_f32_e32 v30, v251, v30
	v_mul_f32_e32 v31, v251, v31
	v_mul_f32_e32 v32, v251, v32
	v_mul_f32_e32 v33, v251, v33
	v_mul_f32_e32 v34, v251, v34
	v_mul_f32_e32 v35, v251, v35
	v_mul_f32_e32 v36, v251, v36
	v_mul_f32_e32 v37, v251, v37
	v_mul_f32_e32 v38, v251, v38
	v_mul_f32_e32 v39, v251, v39
	v_mul_f32_e32 v40, v251, v40
	v_mul_f32_e32 v41, v251, v41
	v_mul_f32_e32 v42, v251, v42
	v_mul_f32_e32 v43, v251, v43
	v_mul_f32_e32 v44, v251, v44
	v_mul_f32_e32 v45, v251, v45
	v_mul_f32_e32 v46, v251, v46
	v_mul_f32_e32 v47, v251, v47
	v_mul_f32_e32 v48, v251, v48
	v_mul_f32_e32 v49, v251, v49
	v_mul_f32_e32 v50, v251, v50
	v_mul_f32_e32 v51, v251, v51
	v_mul_f32_e32 v52, v251, v52
	v_mul_f32_e32 v53, v251, v53
	v_mul_f32_e32 v54, v251, v54
	v_mul_f32_e32 v55, v251, v55
	v_mul_f32_e32 v56, v251, v56
	v_mul_f32_e32 v57, v251, v57
	v_mul_f32_e32 v58, v251, v58
	v_mul_f32_e32 v59, v251, v59
	v_mul_f32_e32 v60, v251, v60
	v_mul_f32_e32 v61, v251, v61
	v_mul_f32_e32 v62, v251, v62
	v_mul_f32_e32 v63, v251, v63
	v_mul_f32_e32 v192, v251, v192
	v_sub_f32_e32 v80, v80, v250
	v_sub_f32_e32 v81, v81, v250
	v_sub_f32_e32 v82, v82, v250
	v_sub_f32_e32 v83, v83, v250
	v_sub_f32_e32 v84, v84, v250
	v_sub_f32_e32 v85, v85, v250
	v_sub_f32_e32 v86, v86, v250
	v_sub_f32_e32 v87, v87, v250
	v_sub_f32_e32 v88, v88, v250
	v_sub_f32_e32 v89, v89, v250
	v_sub_f32_e32 v90, v90, v250
	v_sub_f32_e32 v91, v91, v250
	v_sub_f32_e32 v92, v92, v250
	v_sub_f32_e32 v93, v93, v250
	v_sub_f32_e32 v94, v94, v250
	v_sub_f32_e32 v95, v95, v250
	v_sub_f32_e32 v64, v64, v250
	v_sub_f32_e32 v65, v65, v250
	v_sub_f32_e32 v66, v66, v250
	v_sub_f32_e32 v67, v67, v250
	v_sub_f32_e32 v68, v68, v250
	v_sub_f32_e32 v69, v69, v250
	v_sub_f32_e32 v70, v70, v250
	v_sub_f32_e32 v71, v71, v250
	v_sub_f32_e32 v72, v72, v250
	v_sub_f32_e32 v73, v73, v250
	v_sub_f32_e32 v74, v74, v250
	v_sub_f32_e32 v75, v75, v250
	v_sub_f32_e32 v76, v76, v250
	v_sub_f32_e32 v77, v77, v250
	v_sub_f32_e32 v78, v78, v250
	v_sub_f32_e32 v79, v79, v250
	v_sub_f32_e32 v232, v232, v250
	v_sub_f32_e32 v233, v233, v250
	v_sub_f32_e32 v234, v234, v250
	v_sub_f32_e32 v235, v235, v250
	v_sub_f32_e32 v236, v236, v250
	v_sub_f32_e32 v237, v237, v250
	v_sub_f32_e32 v238, v238, v250
	v_sub_f32_e32 v239, v239, v250
	v_sub_f32_e32 v240, v240, v250
	v_sub_f32_e32 v241, v241, v250
	v_sub_f32_e32 v242, v242, v250
	v_sub_f32_e32 v243, v243, v250
	v_sub_f32_e32 v244, v244, v250
	v_sub_f32_e32 v245, v245, v250
	v_sub_f32_e32 v246, v246, v250
	v_sub_f32_e32 v247, v247, v250
	v_exp_f32_e32 v156, v80
	v_exp_f32_e32 v157, v81
	v_exp_f32_e32 v158, v82
	v_exp_f32_e32 v159, v83
	v_exp_f32_e32 v160, v84
	v_exp_f32_e32 v161, v85
	v_exp_f32_e32 v162, v86
	v_exp_f32_e32 v163, v87
	v_exp_f32_e32 v214, v88
	v_exp_f32_e32 v215, v89
	v_exp_f32_e32 v216, v90
	v_exp_f32_e32 v217, v91
	v_exp_f32_e32 v218, v92
	v_exp_f32_e32 v219, v93
	v_exp_f32_e32 v220, v94
	v_exp_f32_e32 v221, v95
	s_nop 0
	v_add_f32_e32 v253, v157, v156
	v_add_f32_e32 v253, v158, v253
	v_add_f32_e32 v253, v159, v253
	v_add_f32_e32 v253, v160, v253
	v_add_f32_e32 v253, v161, v253
	v_add_f32_e32 v253, v162, v253
	v_add_f32_e32 v253, v163, v253
	v_add_f32_e32 v253, v214, v253
	v_add_f32_e32 v253, v215, v253
	v_add_f32_e32 v253, v216, v253
	v_add_f32_e32 v253, v217, v253
	v_add_f32_e32 v253, v218, v253
	v_add_f32_e32 v253, v219, v253
	v_add_f32_e32 v253, v220, v253
	v_add_f32_e32 v190, v221, v253
	v_cvt_pk_bf16_f32 v144, v156, v157
	v_cvt_pk_bf16_f32 v145, v158, v159
	v_cvt_pk_bf16_f32 v146, v160, v161
	v_cvt_pk_bf16_f32 v147, v162, v163
	v_cvt_pk_bf16_f32 v148, v214, v215
	v_cvt_pk_bf16_f32 v149, v216, v217
	v_cvt_pk_bf16_f32 v150, v218, v219
	v_cvt_pk_bf16_f32 v151, v220, v221

.LBB0_174:
	ds_read_b128 v[80:83], v178
	ds_read_b128 v[84:87], v155 offset:4096
	ds_read_b128 v[88:91], v178 offset:8192
	ds_read_b128 v[92:95], v155 offset:12288
	v_add_f32_e32 v192, v190, v192
	s_waitcnt lgkmcnt(8)
	v_mfma_f32_32x32x16_bf16 v[48:63], v[132:135], v[144:147], v[48:63]
	v_exp_f32_e32 v156, v64
	v_exp_f32_e32 v157, v65
	s_waitcnt lgkmcnt(7)
	v_mfma_f32_32x32x16_bf16 v[32:47], v[128:131], v[144:147], v[32:47]
	v_exp_f32_e32 v158, v66
	v_exp_f32_e32 v159, v67
	s_waitcnt lgkmcnt(6)
	v_mfma_f32_32x32x16_bf16 v[16:31], v[136:139], v[144:147], v[16:31]
	v_exp_f32_e32 v160, v68
	v_exp_f32_e32 v161, v69
	s_waitcnt lgkmcnt(5)
	v_mfma_f32_32x32x16_bf16 v[0:15], v[140:143], v[144:147], v[0:15]
	s_add_i32 s7, s84, 0
	s_add_i32 s8, s36, s7
	v_add3_u32 v128, s8, v186, v174
	ds_read_b128 v[144:147], v128 offset:8704
	ds_read_b128 v[198:201], v128 offset:8736
	ds_read_b128 v[224:227], v128 offset:8768
	ds_read_b128 v[228:231], v128 offset:8800
	v_exp_f32_e32 v162, v70
	v_exp_f32_e32 v163, v71
	s_waitcnt lgkmcnt(7)
	v_mfma_f32_32x32x16_bf16 v[48:63], v[80:83], v[148:151], v[48:63]
	v_add_u32_e32 v190, s7, v188
	v_xor_b32_e32 v191, 64, v190
	ds_read_b128 v[128:131], v190
	ds_read_b128 v[132:135], v191 offset:4096
	ds_read_b128 v[136:139], v190 offset:8192
	ds_read_b128 v[140:143], v191 offset:12288
	v_exp_f32_e32 v214, v72
	v_exp_f32_e32 v215, v73
	s_waitcnt lgkmcnt(10)
	v_mfma_f32_32x32x16_bf16 v[32:47], v[84:87], v[148:151], v[32:47]
	v_exp_f32_e32 v216, v74
	v_exp_f32_e32 v217, v75
	s_waitcnt lgkmcnt(9)
	v_mfma_f32_32x32x16_bf16 v[16:31], v[88:91], v[148:151], v[16:31]
	v_exp_f32_e32 v218, v76
	v_exp_f32_e32 v219, v77
	s_waitcnt lgkmcnt(8)
	v_mfma_f32_32x32x16_bf16 v[0:15], v[92:95], v[148:151], v[0:15]
	v_exp_f32_e32 v220, v78
	v_exp_f32_e32 v221, v79
	s_waitcnt lgkmcnt(7)
	v_mfma_f32_32x32x16_bf16 v[80:95], v[144:147], v[104:107], v[232:247]
	v_add_f32_e32 v253, v157, v156
	v_add_f32_e32 v253, v158, v253
	v_add_f32_e32 v253, v159, v253
	v_cvt_pk_bf16_f32 v148, v214, v215
	v_cvt_pk_bf16_f32 v149, v216, v217
	s_waitcnt lgkmcnt(6)
	v_mfma_f32_32x32x16_bf16 v[80:95], v[198:201], v[96:99], v[80:95]
	v_add_f32_e32 v253, v160, v253
	v_add_f32_e32 v253, v161, v253
	v_add_f32_e32 v253, v162, v253
	v_add_f32_e32 v253, v163, v253
	v_cvt_pk_bf16_f32 v150, v218, v219
	v_cvt_pk_bf16_f32 v151, v220, v221
	s_waitcnt lgkmcnt(5)
	v_mfma_f32_32x32x16_bf16 v[80:95], v[224:227], v[100:103], v[80:95]
	v_add_f32_e32 v253, v214, v253
	v_add_f32_e32 v253, v215, v253
	v_add_f32_e32 v253, v216, v253
	v_add_f32_e32 v253, v217, v253
	v_cvt_pk_bf16_f32 v144, v156, v157
	v_cvt_pk_bf16_f32 v145, v158, v159
	s_waitcnt lgkmcnt(4)
	v_mfma_f32_32x32x16_bf16 v[80:95], v[228:231], v[108:111], v[80:95]
	v_add_f32_e32 v253, v218, v253
	v_add_f32_e32 v253, v219, v253
	v_add_f32_e32 v253, v220, v253
	v_add_f32_e32 v193, v221, v253
	v_cvt_pk_bf16_f32 v146, v160, v161
	v_cvt_pk_bf16_f32 v147, v162, v163
	v_cmp_ngt_f32_e32 vcc, s68, v193
	s_cbranch_vccz .LBB0_177
	v_max3_f32 v250, v64, v65, v66
	v_max3_f32 v251, v67, v68, v69
	v_max3_f32 v250, v250, v70, v71
	v_max3_f32 v251, v251, v72, v73
	v_max3_f32 v250, v250, v74, v75
	v_max3_f32 v251, v251, v76, v77
	v_max3_f32 v250, v250, v78, v79
	v_max_f32_e32 v250, v250, v251
	v_mov_b32_e32 v251, v250
	s_nop 1
	v_permlane32_swap_b32_e32 v250, v251
	v_max_f32_e32 v250, v250, v251
	v_cmp_lt_f32_e32 vcc, v154, v250
	s_cbranch_vccz .LBB0_177
	s_nop 1
	v_cndmask_b32_e32 v250, 0, v250, vcc
	v_sub_f32_e32 v251, 0, v250
	v_exp_f32_e32 v251, v251
	s_nop 0
	v_mul_f32_e32 v0, v251, v0
	v_mul_f32_e32 v1, v251, v1
	v_mul_f32_e32 v2, v251, v2
	v_mul_f32_e32 v3, v251, v3
	v_mul_f32_e32 v4, v251, v4
	v_mul_f32_e32 v5, v251, v5
	v_mul_f32_e32 v6, v251, v6
	v_mul_f32_e32 v7, v251, v7
	v_mul_f32_e32 v8, v251, v8
	v_mul_f32_e32 v9, v251, v9
	v_mul_f32_e32 v10, v251, v10
	v_mul_f32_e32 v11, v251, v11
	v_mul_f32_e32 v12, v251, v12
	v_mul_f32_e32 v13, v251, v13
	v_mul_f32_e32 v14, v251, v14
	v_mul_f32_e32 v15, v251, v15
	v_mul_f32_e32 v16, v251, v16
	v_mul_f32_e32 v17, v251, v17
	v_mul_f32_e32 v18, v251, v18
	v_mul_f32_e32 v19, v251, v19
	v_mul_f32_e32 v20, v251, v20
	v_mul_f32_e32 v21, v251, v21
	v_mul_f32_e32 v22, v251, v22
	v_mul_f32_e32 v23, v251, v23
	v_mul_f32_e32 v24, v251, v24
	v_mul_f32_e32 v25, v251, v25
	v_mul_f32_e32 v26, v251, v26
	v_mul_f32_e32 v27, v251, v27
	v_mul_f32_e32 v28, v251, v28
	v_mul_f32_e32 v29, v251, v29
	v_mul_f32_e32 v30, v251, v30
	v_mul_f32_e32 v31, v251, v31
	v_mul_f32_e32 v32, v251, v32
	v_mul_f32_e32 v33, v251, v33
	v_mul_f32_e32 v34, v251, v34
	v_mul_f32_e32 v35, v251, v35
	v_mul_f32_e32 v36, v251, v36
	v_mul_f32_e32 v37, v251, v37
	v_mul_f32_e32 v38, v251, v38
	v_mul_f32_e32 v39, v251, v39
	v_mul_f32_e32 v40, v251, v40
	v_mul_f32_e32 v41, v251, v41
	v_mul_f32_e32 v42, v251, v42
	v_mul_f32_e32 v43, v251, v43
	v_mul_f32_e32 v44, v251, v44
	v_mul_f32_e32 v45, v251, v45
	v_mul_f32_e32 v46, v251, v46
	v_mul_f32_e32 v47, v251, v47
	v_mul_f32_e32 v48, v251, v48
	v_mul_f32_e32 v49, v251, v49
	v_mul_f32_e32 v50, v251, v50
	v_mul_f32_e32 v51, v251, v51
	v_mul_f32_e32 v52, v251, v52
	v_mul_f32_e32 v53, v251, v53
	v_mul_f32_e32 v54, v251, v54
	v_mul_f32_e32 v55, v251, v55
	v_mul_f32_e32 v56, v251, v56
	v_mul_f32_e32 v57, v251, v57
	v_mul_f32_e32 v58, v251, v58
	v_mul_f32_e32 v59, v251, v59
	v_mul_f32_e32 v60, v251, v60
	v_mul_f32_e32 v61, v251, v61
	v_mul_f32_e32 v62, v251, v62
	v_mul_f32_e32 v63, v251, v63
	v_mul_f32_e32 v192, v251, v192
	v_sub_f32_e32 v64, v64, v250
	v_sub_f32_e32 v65, v65, v250
	v_sub_f32_e32 v66, v66, v250
	v_sub_f32_e32 v67, v67, v250
	v_sub_f32_e32 v68, v68, v250
	v_sub_f32_e32 v69, v69, v250
; #define DA_LOAD(j) do { const bf16_t* t_ = kvbase + (size_t)(j) * 64 * 4096; kreg0 = *(const u32x4*)(t_ + kgo); kreg1 = *(const u32x4*)(t_ + (kgo + 32u * 4096u)); vreg0 = *(const u32x4*)(t_ + vgo); vreg1 = *(const u32x4*)(t_ + (vgo + 4096u)); } while (0)
; __device__ __forceinline__ void da_unit(LAS unsigned char* lds, const bf16_t* __restrict__ proj, bf16_t* __restrict__ y, int unit,
;                                         const float* __restrict__ t5, float lam, float one_m_li, const float* __restrict__ subg) {
;     ...
; #pragma unroll 2
;     for (int j = 0; j < 64; ++j) {
;         const int j1 = j + 1;
;         const bool near1 = (64 * j1 + 63 >= qblk - 128) && (64 * j1 <= qblk + 255);
;         const float bc1 = tbl[(64 * j1 > qblk) ? 256 : 0]; const int dtoff1 = (64 * j1 > qblk) ? DA_DR_OFF : DA_DL_OFF;
;         DA_STEP(sa, sb, pp0, pp1, pc0, pc1, lds + bprev, 1, lds + bcur, 1, j * 64, lds + bcur, 0);
;         __syncthreads();
;         DA_STORE(lds + bnn); { const int jl = j + 3 < 64 ? j + 3 : 63; DA_LOAD(jl); }
	v_sub_f32_e32 v70, v70, v250
	v_sub_f32_e32 v71, v71, v250
	v_sub_f32_e32 v72, v72, v250
	v_sub_f32_e32 v73, v73, v250
	v_sub_f32_e32 v74, v74, v250
	v_sub_f32_e32 v75, v75, v250
	v_sub_f32_e32 v76, v76, v250
	v_sub_f32_e32 v77, v77, v250
	v_sub_f32_e32 v78, v78, v250
	v_sub_f32_e32 v79, v79, v250
	v_sub_f32_e32 v80, v80, v250
	v_sub_f32_e32 v81, v81, v250
	v_sub_f32_e32 v82, v82, v250
	v_sub_f32_e32 v83, v83, v250
	v_sub_f32_e32 v84, v84, v250
	v_sub_f32_e32 v85, v85, v250
	v_sub_f32_e32 v86, v86, v250
	v_sub_f32_e32 v87, v87, v250
	v_sub_f32_e32 v88, v88, v250
	v_sub_f32_e32 v89, v89, v250
	v_sub_f32_e32 v90, v90, v250
	v_sub_f32_e32 v91, v91, v250
	v_sub_f32_e32 v92, v92, v250
	v_sub_f32_e32 v93, v93, v250
	v_sub_f32_e32 v94, v94, v250
	v_sub_f32_e32 v95, v95, v250
	v_sub_f32_e32 v232, v232, v250
	v_sub_f32_e32 v233, v233, v250
	v_sub_f32_e32 v234, v234, v250
	v_sub_f32_e32 v235, v235, v250
	v_sub_f32_e32 v236, v236, v250
	v_sub_f32_e32 v237, v237, v250
	v_sub_f32_e32 v238, v238, v250
	v_sub_f32_e32 v239, v239, v250
	v_sub_f32_e32 v240, v240, v250
	v_sub_f32_e32 v241, v241, v250
	v_sub_f32_e32 v242, v242, v250
	v_sub_f32_e32 v243, v243, v250
	v_sub_f32_e32 v244, v244, v250
	v_sub_f32_e32 v245, v245, v250
	v_sub_f32_e32 v246, v246, v250
	v_sub_f32_e32 v247, v247, v250
	v_exp_f32_e32 v156, v64
	v_exp_f32_e32 v157, v65
	v_exp_f32_e32 v158, v66
	v_exp_f32_e32 v159, v67
	v_exp_f32_e32 v160, v68
	v_exp_f32_e32 v161, v69
	v_exp_f32_e32 v162, v70
	v_exp_f32_e32 v163, v71
	v_exp_f32_e32 v214, v72
	v_exp_f32_e32 v215, v73
	v_exp_f32_e32 v216, v74
	v_exp_f32_e32 v217, v75
	v_exp_f32_e32 v218, v76
	v_exp_f32_e32 v219, v77
	v_exp_f32_e32 v220, v78
	v_exp_f32_e32 v221, v79
	s_nop 0
	v_add_f32_e32 v253, v157, v156
	v_add_f32_e32 v253, v158, v253
	v_add_f32_e32 v253, v159, v253
	v_add_f32_e32 v253, v160, v253
	v_add_f32_e32 v253, v161, v253
	v_add_f32_e32 v253, v162, v253
	v_add_f32_e32 v253, v163, v253
	v_add_f32_e32 v253, v214, v253
	v_add_f32_e32 v253, v215, v253
	v_add_f32_e32 v253, v216, v253
	v_add_f32_e32 v253, v217, v253
	v_add_f32_e32 v253, v218, v253
	v_add_f32_e32 v253, v219, v253
	v_add_f32_e32 v253, v220, v253
	v_add_f32_e32 v193, v221, v253
	v_cvt_pk_bf16_f32 v144, v156, v157
	v_cvt_pk_bf16_f32 v145, v158, v159
	v_cvt_pk_bf16_f32 v146, v160, v161
	v_cvt_pk_bf16_f32 v147, v162, v163
	v_cvt_pk_bf16_f32 v148, v214, v215
	v_cvt_pk_bf16_f32 v149, v216, v217
	v_cvt_pk_bf16_f32 v150, v218, v219
	v_cvt_pk_bf16_f32 v151, v220, v221
.LBB0_177:
	v_add_u32_e32 v64, s87, v175
	s_waitcnt lgkmcnt(0)
	s_barrier
	s_waitcnt vmcnt(3)
	ds_write_b128 v64, v[116:119]
	s_waitcnt vmcnt(2)
	ds_write_b128 v64, v[124:127] offset:8704
	v_add_u32_e32 v64, s87, v184
	s_min_u32 s7, s37, 60
	s_waitcnt vmcnt(0)
	v_perm_b32 v65, v120, v112, s66
	v_perm_b32 v66, v120, v112, s67
	v_add_u32_e32 v64, 0x4400, v64
	s_lshl_b32 s7, s7, 19
	ds_write2_b32 v64, v65, v66 offset1:32
	v_add_u32_e32 v65, s87, v185
	s_add_u32 s7, s30, s7
	v_perm_b32 v66, v121, v113, s66
	v_perm_b32 v67, v121, v113, s67
	v_add_u32_e32 v65, 0x4400, v65
	s_addc_u32 s9, s31, 0
	ds_write2_b32 v65, v66, v67 offset0:64 offset1:96
	v_perm_b32 v66, v122, v114, s66
	v_perm_b32 v67, v122, v114, s67
	s_add_u32 s8, s7, 0x180000
	ds_write2_b32 v64, v66, v67 offset0:128 offset1:160
	v_perm_b32 v64, v123, v115, s66
	v_perm_b32 v66, v123, v115, s67
	s_addc_u32 s9, s9, 0
	ds_write2_b32 v65, v64, v66 offset0:192 offset1:224
	global_load_dwordx4 v[116:119], v254, s[8:9]
	global_load_dwordx4 v[120:123], v169, s[8:9]
	global_load_dwordx4 v[112:115], v173, s[8:9]
	global_load_dwordx4 v[124:127], v171, s[8:9]
	v_cmp_neq_f32_e32 vcc, v177, v179
	s_cbranch_vccz .Lda_bcskip4
	s_nop 0
	v_sub_f32_e32 v250, v177, v179
	v_add_f32_e32 v232, v232, v250
	v_add_f32_e32 v233, v233, v250
	v_add_f32_e32 v234, v234, v250
	v_add_f32_e32 v235, v235, v250
	v_add_f32_e32 v236, v236, v250
	v_add_f32_e32 v237, v237, v250
	v_add_f32_e32 v238, v238, v250
	v_add_f32_e32 v239, v239, v250
	v_add_f32_e32 v240, v240, v250
	v_add_f32_e32 v241, v241, v250
	v_add_f32_e32 v242, v242, v250
	v_add_f32_e32 v243, v243, v250
	v_add_f32_e32 v244, v244, v250
	v_add_f32_e32 v245, v245, v250
	v_add_f32_e32 v246, v246, v250
	v_add_f32_e32 v247, v247, v250
.Lda_bcskip4:
	s_cmp_gt_i32 s85, s77
	s_cselect_b64 s[8:9], -1, 0
	s_addk_i32 s86, 0xff81
	s_cmpk_gt_i32 s86, 0x7f
	s_cselect_b64 s[86:87], -1, 0
	s_or_b64 s[8:9], s[8:9], s[86:87]
	s_and_b64 vcc, exec, s[8:9]
	s_cbranch_vccnz .LBB0_179
	s_addk_i32 s6, 0x600
	v_add_u32_e32 v78, s6, v189
	ds_read2_b32 v[64:65], v78 offset0:48 offset1:49
	ds_read2_b32 v[66:67], v78 offset0:50 offset1:51
	ds_read2_b32 v[68:69], v78 offset0:56 offset1:57
	ds_read2_b32 v[70:71], v78 offset0:58 offset1:59
	ds_read2_b32 v[72:73], v78 offset0:32 offset1:33
	ds_read2_b32 v[74:75], v78 offset0:34 offset1:35
	ds_read2_b32 v[76:77], v78 offset0:40 offset1:41
	ds_read2_b32 v[78:79], v78 offset0:42 offset1:43
	s_waitcnt lgkmcnt(4)
	v_pk_add_f32 v[94:95], v[94:95], v[70:71]
	v_pk_add_f32 v[92:93], v[92:93], v[68:69]
	v_pk_add_f32 v[90:91], v[90:91], v[66:67]
	v_pk_add_f32 v[88:89], v[88:89], v[64:65]
	s_waitcnt lgkmcnt(0)
	v_pk_add_f32 v[86:87], v[86:87], v[78:79]
	v_pk_add_f32 v[84:85], v[84:85], v[76:77]
	v_pk_add_f32 v[82:83], v[82:83], v[74:75]
	v_pk_add_f32 v[80:81], v[80:81], v[72:73]
.LBB0_179:
	v_xor_b32_e32 v72, 32, v190
	v_xor_b32_e32 v76, 0x60, v190
	ds_read_b128 v[64:67], v72
	ds_read_b128 v[68:71], v76 offset:4096
	ds_read_b128 v[72:75], v72 offset:8192
	ds_read_b128 v[76:79], v76 offset:12288
	v_add_f32_e32 v155, v193, v192
	v_mfma_f32_32x32x16_bf16 v[48:63], v[128:131], v[144:147], v[48:63]
	v_exp_f32_e32 v156, v80
	v_exp_f32_e32 v157, v81
	v_mfma_f32_32x32x16_bf16 v[32:47], v[132:135], v[144:147], v[32:47]
	v_exp_f32_e32 v158, v82
	v_exp_f32_e32 v159, v83
	v_mfma_f32_32x32x16_bf16 v[16:31], v[136:139], v[144:147], v[16:31]
	v_exp_f32_e32 v160, v84
	v_exp_f32_e32 v161, v85
	v_mfma_f32_32x32x16_bf16 v[0:15], v[140:143], v[144:147], v[0:15]
	v_add_u32_e32 v128, s83, v187
	ds_read_b128 v[144:147], v128
	ds_read_b128 v[192:195], v128 offset:32
	ds_read_b128 v[198:201], v128 offset:64
	ds_read_b128 v[224:227], v128 offset:96
	v_exp_f32_e32 v162, v86
	v_exp_f32_e32 v163, v87
	s_waitcnt lgkmcnt(7)
	v_mfma_f32_32x32x16_bf16 v[48:63], v[64:67], v[148:151], v[48:63]
	ds_read_b128 v[140:143], v191
	ds_read_b128 v[136:139], v190 offset:4096
	ds_read_b128 v[132:135], v191 offset:8192
	ds_read_b128 v[128:131], v190 offset:12288
	v_exp_f32_e32 v214, v88
	v_exp_f32_e32 v215, v89
	s_waitcnt lgkmcnt(10)
	v_mfma_f32_32x32x16_bf16 v[32:47], v[68:71], v[148:151], v[32:47]
	v_exp_f32_e32 v216, v90
	v_exp_f32_e32 v217, v91
	s_waitcnt lgkmcnt(9)
	v_mfma_f32_32x32x16_bf16 v[16:31], v[72:75], v[148:151], v[16:31]
	v_exp_f32_e32 v218, v92
	v_exp_f32_e32 v219, v93
	s_waitcnt lgkmcnt(8)
	v_mfma_f32_32x32x16_bf16 v[0:15], v[76:79], v[148:151], v[0:15]
	v_exp_f32_e32 v220, v94
	v_exp_f32_e32 v221, v95
	s_waitcnt lgkmcnt(7)
	v_mfma_f32_32x32x16_bf16 v[64:79], v[144:147], v[104:107], v[232:247]
	v_add_f32_e32 v253, v157, v156
	v_add_f32_e32 v253, v158, v253
	v_add_f32_e32 v253, v159, v253
	v_cvt_pk_bf16_f32 v148, v156, v157
	v_cvt_pk_bf16_f32 v149, v158, v159
	s_waitcnt lgkmcnt(6)
	v_mfma_f32_32x32x16_bf16 v[64:79], v[192:195], v[96:99], v[64:79]
	v_add_f32_e32 v253, v160, v253
	v_add_f32_e32 v253, v161, v253
	v_add_f32_e32 v253, v162, v253
	v_add_f32_e32 v253, v163, v253
	v_cvt_pk_bf16_f32 v150, v160, v161
	v_cvt_pk_bf16_f32 v151, v162, v163
	s_waitcnt lgkmcnt(5)
	v_mfma_f32_32x32x16_bf16 v[64:79], v[198:201], v[100:103], v[64:79]
	v_add_f32_e32 v253, v214, v253
	v_add_f32_e32 v253, v215, v253
	v_add_f32_e32 v253, v216, v253
	v_add_f32_e32 v253, v217, v253
	v_cvt_pk_bf16_f32 v144, v214, v215
	v_cvt_pk_bf16_f32 v145, v216, v217
	s_waitcnt lgkmcnt(4)
	v_mfma_f32_32x32x16_bf16 v[64:79], v[224:227], v[108:111], v[64:79]
	v_add_f32_e32 v253, v218, v253
	v_add_f32_e32 v253, v219, v253
	v_add_f32_e32 v253, v220, v253
	v_add_f32_e32 v178, v221, v253
	v_cvt_pk_bf16_f32 v146, v218, v219
	v_cvt_pk_bf16_f32 v147, v220, v221
	v_cmp_ngt_f32_e32 vcc, s68, v178
	s_cbranch_vccz .LBB0_182
	v_max3_f32 v250, v80, v81, v82
	v_max3_f32 v251, v83, v84, v85
	v_max3_f32 v250, v250, v86, v87
	v_max3_f32 v251, v251, v88, v89
	v_max3_f32 v250, v250, v90, v91
	v_max3_f32 v251, v251, v92, v93
	v_max3_f32 v250, v250, v94, v95
	v_max_f32_e32 v250, v250, v251
	v_mov_b32_e32 v251, v250
	s_nop 1
	v_permlane32_swap_b32_e32 v250, v251
	v_max_f32_e32 v250, v250, v251
	v_cmp_lt_f32_e32 vcc, v154, v250
	s_cbranch_vccz .LBB0_182
	s_nop 1
	v_cndmask_b32_e32 v250, 0, v250, vcc
	v_sub_f32_e32 v251, 0, v250
	v_exp_f32_e32 v251, v251
	s_nop 0
	v_mul_f32_e32 v0, v251, v0
	v_mul_f32_e32 v1, v251, v1
	v_mul_f32_e32 v2, v251, v2
	v_mul_f32_e32 v3, v251, v3
	v_mul_f32_e32 v4, v251, v4
	v_mul_f32_e32 v5, v251, v5
	v_mul_f32_e32 v6, v251, v6
	v_mul_f32_e32 v7, v251, v7
	v_mul_f32_e32 v8, v251, v8
	v_mul_f32_e32 v9, v251, v9
	v_mul_f32_e32 v10, v251, v10
	v_mul_f32_e32 v11, v251, v11
	v_mul_f32_e32 v12, v251, v12
	v_mul_f32_e32 v13, v251, v13
	v_mul_f32_e32 v14, v251, v14
	v_mul_f32_e32 v15, v251, v15
	v_mul_f32_e32 v16, v251, v16
	v_mul_f32_e32 v17, v251, v17
	v_mul_f32_e32 v18, v251, v18
	v_mul_f32_e32 v19, v251, v19
	v_mul_f32_e32 v20, v251, v20
	v_mul_f32_e32 v21, v251, v21
	v_mul_f32_e32 v22, v251, v22
	v_mul_f32_e32 v23, v251, v23
	v_mul_f32_e32 v24, v251, v24
	v_mul_f32_e32 v25, v251, v25
	v_mul_f32_e32 v26, v251, v26
	v_mul_f32_e32 v27, v251, v27
	v_mul_f32_e32 v28, v251, v28
	v_mul_f32_e32 v29, v251, v29
	v_mul_f32_e32 v30, v251, v30
	v_mul_f32_e32 v31, v251, v31
	v_mul_f32_e32 v32, v251, v32
	v_mul_f32_e32 v33, v251, v33
	v_mul_f32_e32 v34, v251, v34
	v_mul_f32_e32 v35, v251, v35
	v_mul_f32_e32 v36, v251, v36
	v_mul_f32_e32 v37, v251, v37
	v_mul_f32_e32 v38, v251, v38
	v_mul_f32_e32 v39, v251, v39
	v_mul_f32_e32 v40, v251, v40
	v_mul_f32_e32 v41, v251, v41
	v_mul_f32_e32 v42, v251, v42
	v_mul_f32_e32 v43, v251, v43
	v_mul_f32_e32 v44, v251, v44
	v_mul_f32_e32 v45, v251, v45
	v_mul_f32_e32 v46, v251, v46
	v_mul_f32_e32 v47, v251, v47
	v_mul_f32_e32 v48, v251, v48
	v_mul_f32_e32 v49, v251, v49
	v_mul_f32_e32 v50, v251, v50
	v_mul_f32_e32 v51, v251, v51
	v_mul_f32_e32 v52, v251, v52
	v_mul_f32_e32 v53, v251, v53
	v_mul_f32_e32 v54, v251, v54
	v_mul_f32_e32 v55, v251, v55
	v_mul_f32_e32 v56, v251, v56
	v_mul_f32_e32 v57, v251, v57
	v_mul_f32_e32 v58, v251, v58
	v_mul_f32_e32 v59, v251, v59
	v_mul_f32_e32 v60, v251, v60
	v_mul_f32_e32 v61, v251, v61
	v_mul_f32_e32 v62, v251, v62
	v_mul_f32_e32 v63, v251, v63
	v_mul_f32_e32 v155, v251, v155
	v_sub_f32_e32 v80, v80, v250
	v_sub_f32_e32 v81, v81, v250
	v_sub_f32_e32 v82, v82, v250
	v_sub_f32_e32 v83, v83, v250
	v_sub_f32_e32 v84, v84, v250
	v_sub_f32_e32 v85, v85, v250
	v_sub_f32_e32 v86, v86, v250
	v_sub_f32_e32 v87, v87, v250
	v_sub_f32_e32 v88, v88, v250
	v_sub_f32_e32 v89, v89, v250
	v_sub_f32_e32 v90, v90, v250
	v_sub_f32_e32 v91, v91, v250
	v_sub_f32_e32 v92, v92, v250
	v_sub_f32_e32 v93, v93, v250
	v_sub_f32_e32 v94, v94, v250
	v_sub_f32_e32 v95, v95, v250
	v_sub_f32_e32 v64, v64, v250
	v_sub_f32_e32 v65, v65, v250
	v_sub_f32_e32 v66, v66, v250
	v_sub_f32_e32 v67, v67, v250
	v_sub_f32_e32 v68, v68, v250
	v_sub_f32_e32 v69, v69, v250
	v_sub_f32_e32 v70, v70, v250
	v_sub_f32_e32 v71, v71, v250
	v_sub_f32_e32 v72, v72, v250
	v_sub_f32_e32 v73, v73, v250
	v_sub_f32_e32 v74, v74, v250
	v_sub_f32_e32 v75, v75, v250
	v_sub_f32_e32 v76, v76, v250
	v_sub_f32_e32 v77, v77, v250
	v_sub_f32_e32 v78, v78, v250
	v_sub_f32_e32 v79, v79, v250
	v_sub_f32_e32 v232, v232, v250
	v_sub_f32_e32 v233, v233, v250
	v_sub_f32_e32 v234, v234, v250
	v_sub_f32_e32 v235, v235, v250
	v_sub_f32_e32 v236, v236, v250
	v_sub_f32_e32 v237, v237, v250
	v_sub_f32_e32 v238, v238, v250
	v_sub_f32_e32 v239, v239, v250
	v_sub_f32_e32 v240, v240, v250
	v_sub_f32_e32 v241, v241, v250
	v_sub_f32_e32 v242, v242, v250
	v_sub_f32_e32 v243, v243, v250
	v_sub_f32_e32 v244, v244, v250
	v_sub_f32_e32 v245, v245, v250
	v_sub_f32_e32 v246, v246, v250
	v_sub_f32_e32 v247, v247, v250
	v_exp_f32_e32 v156, v80
	v_exp_f32_e32 v157, v81
	v_exp_f32_e32 v158, v82
	v_exp_f32_e32 v159, v83
	v_exp_f32_e32 v160, v84
	v_exp_f32_e32 v161, v85
	v_exp_f32_e32 v162, v86
	v_exp_f32_e32 v163, v87
	v_exp_f32_e32 v214, v88
	v_exp_f32_e32 v215, v89
	v_exp_f32_e32 v216, v90
	v_exp_f32_e32 v217, v91
	v_exp_f32_e32 v218, v92
	v_exp_f32_e32 v219, v93
	v_exp_f32_e32 v220, v94
	v_exp_f32_e32 v221, v95
	s_nop 0
	v_add_f32_e32 v253, v157, v156
	v_add_f32_e32 v253, v158, v253
	v_add_f32_e32 v253, v159, v253
	v_add_f32_e32 v253, v160, v253
	v_add_f32_e32 v253, v161, v253
	v_add_f32_e32 v253, v162, v253
	v_add_f32_e32 v253, v163, v253
	v_add_f32_e32 v253, v214, v253
	v_add_f32_e32 v253, v215, v253
	v_add_f32_e32 v253, v216, v253
	v_add_f32_e32 v253, v217, v253
	v_add_f32_e32 v253, v218, v253
	v_add_f32_e32 v253, v219, v253
	v_add_f32_e32 v253, v220, v253
	v_add_f32_e32 v178, v221, v253
	v_cvt_pk_bf16_f32 v148, v156, v157
	v_cvt_pk_bf16_f32 v149, v158, v159
	v_cvt_pk_bf16_f32 v150, v160, v161
	v_cvt_pk_bf16_f32 v151, v162, v163
	v_cvt_pk_bf16_f32 v144, v214, v215
	v_cvt_pk_bf16_f32 v145, v216, v217
	v_cvt_pk_bf16_f32 v146, v218, v219
	v_cvt_pk_bf16_f32 v147, v220, v221

; __global__ void __launch_bounds__(512, 2) fwd_megakernel(Args a) {
;     ...
;             for (int u = vcuz; u < 2048; u += G) att::da_unit(lds, proj, yb, u, a.t5, lam, __uint_as_float(__builtin_amdgcn_readfirstlane(__float_as_uint(1.0f - li))), a.subg + lz * 128);
;             for (int u = vcuz; u < 2048; u += G) att::na_unit(lds, proj, yb, u, a.rpb + (size_t)lz * 8 * 465);
.LBB0_190:
	v_lshlrev_b32_e32 v255, 4, v204
	v_add_u32_e32 v255, 0x1b000, v255
	ds_read_b128 v[156:159], v255
	ds_read_b128 v[160:163], v255 offset:8192
	ds_read_b128 v[214:217], v255 offset:20736
	ds_read_b128 v[218:221], v255 offset:28928
	s_waitcnt lgkmcnt(0)
	v_readlane_b32 s76, v249, 5
	v_readlane_b32 s78, v249, 7
	v_readlane_b32 s79, v249, 8
	v_readlane_b32 s82, v249, 11
	v_readlane_b32 s83, v249, 12
	s_mul_hi_i32 s0, s74, 0x3a20
	s_mulk_i32 s74, 0x3a20
	s_mov_b64 s[78:79], s[82:83]
	v_readlane_b32 s80, v249, 9
	v_readlane_b32 s81, v249, 10
	v_readlane_b32 s84, v249, 13
	v_readlane_b32 s85, v249, 14
	v_readlane_b32 s86, v249, 15
	v_readlane_b32 s87, v249, 16
	s_add_u32 s38, s78, s74
	v_readlane_b32 s10, v248, 24
	v_readlane_b32 s72, v248, 26
	v_readlane_b32 s88, v249, 17
	v_readlane_b32 s89, v249, 18
	v_readlane_b32 s90, v249, 19
	v_readlane_b32 s91, v249, 20
	s_mov_b64 s[80:81], s[84:85]
	s_addc_u32 s39, s79, s0
	s_lshl_b32 s74, s12, 2
	v_readlane_b32 s11, v248, 25
	v_readlane_b32 s73, v248, 27
	s_mov_b32 s12, s13
	v_readlane_b32 s77, v249, 6
	s_mov_b64 s[82:83], s[86:87]
	s_mov_b64 s[84:85], s[88:89]
	s_mov_b64 s[86:87], s[90:91]
	s_branch .LBB0_193

; __global__ void __launch_bounds__(512, 2) fwd_megakernel(Args a) {
;     extern __shared__ __attribute__((aligned(16))) unsigned char lds_raw[];
	.amdhsa_kernel _Z14fwd_megakernel4Args
		.amdhsa_group_segment_fixed_size 16384
		.amdhsa_private_segment_fixed_size 0
		.amdhsa_kernarg_size 384
		.amdhsa_user_sgpr_count 2
		.amdhsa_user_sgpr_dispatch_ptr 0
		.amdhsa_user_sgpr_queue_ptr 0
		.amdhsa_user_sgpr_kernarg_segment_ptr 1
		.amdhsa_user_sgpr_dispatch_id 0
		.amdhsa_user_sgpr_kernarg_preload_length 0
		.amdhsa_user_sgpr_kernarg_preload_offset 0
		.amdhsa_user_sgpr_private_segment_size 0
		.amdhsa_uses_dynamic_stack 0
		.amdhsa_enable_private_segment 0
		.amdhsa_system_sgpr_workgroup_id_x 1
		.amdhsa_system_sgpr_workgroup_id_y 0
		.amdhsa_system_sgpr_workgroup_id_z 0
		.amdhsa_system_sgpr_workgroup_info 0
		.amdhsa_system_vgpr_workitem_id 2
		.amdhsa_next_free_vgpr 256
		.amdhsa_next_free_sgpr 102
		.amdhsa_accum_offset 256
		.amdhsa_reserve_vcc 1
		.amdhsa_float_round_mode_32 0
		.amdhsa_float_round_mode_16_64 0
		.amdhsa_float_denorm_mode_32 3
		.amdhsa_float_denorm_mode_16_64 3
		.amdhsa_dx10_clamp 1
		.amdhsa_ieee_mode 1
		.amdhsa_fp16_overflow 0
		.amdhsa_tg_split 0
		.amdhsa_exception_fp_ieee_invalid_op 0
		.amdhsa_exception_fp_denorm_src 0
		.amdhsa_exception_fp_ieee_div_zero 0
		.amdhsa_exception_fp_ieee_overflow 0
		.amdhsa_exception_fp_ieee_underflow 0
		.amdhsa_exception_fp_ieee_inexact 0
		.amdhsa_exception_int_div_zero 0
	.end_amdhsa_kernel

; __global__ void __launch_bounds__(512, 2) fwd_megakernel(Args a) {
;     extern __shared__ __attribute__((aligned(16))) unsigned char lds_raw[];
amdhsa.kernels:
  - .agpr_count:     0
    .args:
      - .offset:         0
        .size:           128
        .value_kind:     by_value
      - .offset:         128
        .size:           4
        .value_kind:     hidden_block_count_x
      - .offset:         132
        .size:           4
        .value_kind:     hidden_block_count_y
      - .offset:         136
        .size:           4
        .value_kind:     hidden_block_count_z
      - .offset:         140
        .size:           2
        .value_kind:     hidden_group_size_x
      - .offset:         142
        .size:           2
        .value_kind:     hidden_group_size_y
      - .offset:         144
        .size:           2
        .value_kind:     hidden_group_size_z
      - .offset:         146
        .size:           2
        .value_kind:     hidden_remainder_x
      - .offset:         148
        .size:           2
        .value_kind:     hidden_remainder_y
      - .offset:         150
        .size:           2
        .value_kind:     hidden_remainder_z
      - .offset:         168
        .size:           8
        .value_kind:     hidden_global_offset_x
      - .offset:         176
        .size:           8
        .value_kind:     hidden_global_offset_y
      - .offset:         184
        .size:           8
        .value_kind:     hidden_global_offset_z
      - .offset:         192
        .size:           2
        .value_kind:     hidden_grid_dims
      - .offset:         216
        .size:           8
        .value_kind:     hidden_multigrid_sync_arg
      - .offset:         248
        .size:           4
        .value_kind:     hidden_dynamic_lds_size
    .group_segment_fixed_size: 16384
    .kernarg_segment_align: 8
    .kernarg_segment_size: 384
    .language:       OpenCL C
    .language_version:
      - 2
      - 0
    .max_flat_workgroup_size: 512
    .name:           _Z14fwd_megakernel4Args
    .private_segment_fixed_size: 0
    .sgpr_count:     108
    .sgpr_spill_count: 107
    .symbol:         _Z14fwd_megakernel4Args.kd
    .uniform_work_group_size: 1
    .uses_dynamic_stack: false
    .vgpr_count:     256
    .vgpr_spill_count: 0
    .wavefront_size: 64
